# K-loop back edge (doc 7.11 variant): counter/pointer/exit-test SALU block moved in front of the loop-end barrier in all six K-loops, branch only after the release (on top of v59)
# baseline (speedup 1.0000x reference)
; #define PG8_STAGE(bufoff, gbase, voff) do { _Pragma("unroll") for (int _i = 0; _i < 2; ++_i) \
;         __builtin_amdgcn_global_load_lds((const unsigned*)((const char*)(gbase) + (voff)[_i]), (LAS unsigned*)(lds + (bufoff) + ldsw + _i * 8192), 16, 0, 0); } while (0)
; #define PG8_LDA(dst, b, h) do { _Pragma("unroll") for (int m = 0; m < 4; ++m) _Pragma("unroll") for (int k = 0; k < 2; ++k) dst[m][k] = *(const LAS bf16x8*)(lds + PG8_SA(b, h) + aoffk[k] + m * 2048); } while (0)
; #define PG8_LDB(dst, b, h) do { _Pragma("unroll") for (int n = 0; n < 2; ++n) _Pragma("unroll") for (int k = 0; k < 2; ++k) dst[n][k] = *(const LAS bf16x8*)(lds + PG8_SB(b, h) + boffk[k] + n * 2048); } while (0)
; #define PG8_WAIT_V(n) asm volatile("s_waitcnt vmcnt(" #n ")" ::: "memory")
; #define PG8_WAIT_L(n) asm volatile("s_waitcnt lgkmcnt(" #n ")" ::: "memory")
; #define PG8_BAR __builtin_amdgcn_s_barrier()
; #define PG8_SCHED __builtin_amdgcn_sched_barrier(0)
; template <class Epi, class Sched, class GemmT>
; __device__ __forceinline__ void gemm_phase(LAS unsigned char* lds, const GemmT& g, const Sched& S, const Epi& E, const int wid) {
;     ...
;                 PG8_LDB(B0, 0, 0); PG8_LDB(B1, 0, 1); PG8_SCHED; PG8_LDA(At, 0, 0); PG8_STAGE(PG8_SA(1, 1), a1 + hstepA, voffA);
;                 PG8_WAIT_V(8); PG8_WAIT_L(0); PG8_BAR; PG8_MMA(0, 0, At, B0); PG8_MMA(0, 1, At, B1); PG8_BAR; PG8_SCHED;
;                 PG8_LDA(At, 0, 1); PG8_STAGE(PG8_SB(0, 0), b2, vB2); PG8_STAGE(PG8_SB(0, 1), b2 + hB2, vB2); PG8_STAGE(PG8_SA(0, 0), a2, vA2);
;                 PG8_WAIT_V(8); PG8_WAIT_L(0); PG8_BAR; PG8_MMA(1, 0, At, B0); PG8_MMA(1, 1, At, B1); PG8_BAR; PG8_SCHED;
.LBB0_361:
	ds_read_b128 v[24:27], v186
	ds_read_b128 v[28:31], v187
	ds_read_b128 v[16:19], v188
	ds_read_b128 v[20:23], v189
	ds_read_b128 v[8:11], v190
	ds_read_b128 v[12:15], v191
	ds_read_b128 v[0:3], v192
	ds_read_b128 v[4:7], v193
	s_add_u32 s41, s56, 0xfff80080
	s_addc_u32 s48, s57, -1
	s_cmp_eq_u32 s40, 28
	s_cselect_b32 s83, s43, s48
	s_cselect_b32 s82, s42, s41
	s_cselect_b32 s59, s37, s39
	s_cselect_b32 s58, s36, s38
	s_add_i32 m0, s12, 0xc000
	ds_read_b128 v[174:177], v194
	ds_read_b128 v[204:207], v194 offset:2048
	ds_read_b128 v[178:181], v195
	ds_read_b128 v[208:211], v195 offset:2048
	ds_read_b128 v[212:215], v194 offset:4096
	ds_read_b128 v[220:223], v194 offset:6144
	ds_read_b128 v[216:219], v195 offset:4096
	ds_read_b128 v[224:227], v195 offset:6144
	global_load_lds_dwordx4 v160, s[56:57]
	s_add_i32 m0, s12, 0xe000
	s_nop 0
	global_load_lds_dwordx4 v164, s[56:57]
	s_waitcnt vmcnt(8)
	s_waitcnt lgkmcnt(0)
	s_waitcnt lgkmcnt(0)
	v_mfma_scale_f32_16x16x128_f8f6f4 v[156:159], v[24:31], v[174:181], v[156:159], v196, v196 op_sel_hi:[0,0,0]
	v_mfma_scale_f32_16x16x128_f8f6f4 v[152:155], v[16:23], v[174:181], v[152:155], v196, v196 op_sel_hi:[0,0,0]
	s_barrier
	s_setprio 3
	v_mfma_scale_f32_16x16x128_f8f6f4 v[136:139], v[16:23], v[204:211], v[136:139], v196, v196 op_sel_hi:[0,0,0]
	v_mfma_scale_f32_16x16x128_f8f6f4 v[140:143], v[24:31], v[204:211], v[140:143], v196, v196 op_sel_hi:[0,0,0]
	v_mfma_scale_f32_16x16x128_f8f6f4 v[124:127], v[24:31], v[212:219], v[124:127], v196, v196 op_sel_hi:[0,0,0]
	v_mfma_scale_f32_16x16x128_f8f6f4 v[120:123], v[16:23], v[212:219], v[120:123], v196, v196 op_sel_hi:[0,0,0]
	v_mfma_scale_f32_16x16x128_f8f6f4 v[104:107], v[16:23], v[220:227], v[104:107], v196, v196 op_sel_hi:[0,0,0]
	v_mfma_scale_f32_16x16x128_f8f6f4 v[108:111], v[24:31], v[220:227], v[108:111], v196, v196 op_sel_hi:[0,0,0]
	s_setprio 0
	s_setprio 3
	v_mfma_scale_f32_16x16x128_f8f6f4 v[148:151], v[8:15], v[174:181], v[148:151], v196, v196 op_sel_hi:[0,0,0]
	v_mfma_scale_f32_16x16x128_f8f6f4 v[144:147], v[0:7], v[174:181], v[144:147], v196, v196 op_sel_hi:[0,0,0]
	v_mfma_scale_f32_16x16x128_f8f6f4 v[128:131], v[0:7], v[204:211], v[128:131], v196, v196 op_sel_hi:[0,0,0]
	v_mfma_scale_f32_16x16x128_f8f6f4 v[132:135], v[8:15], v[204:211], v[132:135], v196, v196 op_sel_hi:[0,0,0]
	v_mfma_scale_f32_16x16x128_f8f6f4 v[116:119], v[8:15], v[212:219], v[116:119], v196, v196 op_sel_hi:[0,0,0]
	v_mfma_scale_f32_16x16x128_f8f6f4 v[112:115], v[0:7], v[212:219], v[112:115], v196, v196 op_sel_hi:[0,0,0]
	v_mfma_scale_f32_16x16x128_f8f6f4 v[96:99], v[0:7], v[220:227], v[96:99], v196, v196 op_sel_hi:[0,0,0]
	v_mfma_scale_f32_16x16x128_f8f6f4 v[100:103], v[8:15], v[220:227], v[100:103], v196, v196 op_sel_hi:[0,0,0]
	s_setprio 0
	s_barrier
	s_add_i32 s41, s64, s68
	s_mov_b32 m0, s41
	ds_read_b128 v[204:207], v194 offset:16384
	ds_read_b128 v[212:215], v194 offset:18432
	ds_read_b128 v[208:211], v195 offset:16384
	ds_read_b128 v[216:219], v195 offset:18432
	ds_read_b128 v[220:223], v194 offset:20480
	ds_read_b128 v[230:233], v194 offset:22528
	ds_read_b128 v[224:227], v195 offset:20480
	ds_read_b128 v[234:237], v195 offset:22528
	global_load_lds_dwordx4 v162, s[58:59]
	s_add_i32 m0, s41, 0x2000
	s_add_u32 s50, s58, 0x80000
	s_addc_u32 s51, s59, 0
	s_add_i32 s41, s65, s68
	global_load_lds_dwordx4 v166, s[58:59]
	s_mov_b32 m0, s41
	s_nop 0
	global_load_lds_dwordx4 v162, s[50:51]
	s_add_i32 m0, s41, 0x2000
	s_nop 0
	global_load_lds_dwordx4 v166, s[50:51]
	s_mov_b32 m0, s12
	s_nop 0
	global_load_lds_dwordx4 v160, s[82:83]
	s_mov_b32 m0, s13
	s_nop 0
	global_load_lds_dwordx4 v164, s[82:83]
	s_waitcnt vmcnt(8)
	s_waitcnt lgkmcnt(0)
	s_waitcnt lgkmcnt(0)
	v_mfma_scale_f32_16x16x128_f8f6f4 v[84:87], v[24:31], v[204:211], v[84:87], v196, v196 op_sel_hi:[0,0,0]
	v_mfma_scale_f32_16x16x128_f8f6f4 v[80:83], v[16:23], v[204:211], v[80:83], v196, v196 op_sel_hi:[0,0,0]
	s_barrier
	s_setprio 3
	v_mfma_scale_f32_16x16x128_f8f6f4 v[64:67], v[16:23], v[212:219], v[64:67], v196, v196 op_sel_hi:[0,0,0]
	v_mfma_scale_f32_16x16x128_f8f6f4 v[68:71], v[24:31], v[212:219], v[68:71], v196, v196 op_sel_hi:[0,0,0]
	v_mfma_scale_f32_16x16x128_f8f6f4 v[52:55], v[24:31], v[220:227], v[52:55], v196, v196 op_sel_hi:[0,0,0]
	v_mfma_scale_f32_16x16x128_f8f6f4 v[48:51], v[16:23], v[220:227], v[48:51], v196, v196 op_sel_hi:[0,0,0]
	v_mfma_scale_f32_16x16x128_f8f6f4 v[32:35], v[16:23], v[230:237], v[32:35], v196, v196 op_sel_hi:[0,0,0]
	v_mfma_scale_f32_16x16x128_f8f6f4 v[36:39], v[24:31], v[230:237], v[36:39], v196, v196 op_sel_hi:[0,0,0]
	s_setprio 0
	s_setprio 3
	v_mfma_scale_f32_16x16x128_f8f6f4 v[92:95], v[8:15], v[204:211], v[92:95], v196, v196 op_sel_hi:[0,0,0]
	v_mfma_scale_f32_16x16x128_f8f6f4 v[88:91], v[0:7], v[204:211], v[88:91], v196, v196 op_sel_hi:[0,0,0]
	v_mfma_scale_f32_16x16x128_f8f6f4 v[72:75], v[0:7], v[212:219], v[72:75], v196, v196 op_sel_hi:[0,0,0]
	v_mfma_scale_f32_16x16x128_f8f6f4 v[76:79], v[8:15], v[212:219], v[76:79], v196, v196 op_sel_hi:[0,0,0]
	v_mfma_scale_f32_16x16x128_f8f6f4 v[60:63], v[8:15], v[220:227], v[60:63], v196, v196 op_sel_hi:[0,0,0]
	v_mfma_scale_f32_16x16x128_f8f6f4 v[56:59], v[0:7], v[220:227], v[56:59], v196, v196 op_sel_hi:[0,0,0]
	v_mfma_scale_f32_16x16x128_f8f6f4 v[40:43], v[0:7], v[230:237], v[40:43], v196, v196 op_sel_hi:[0,0,0]
	v_mfma_scale_f32_16x16x128_f8f6f4 v[44:47], v[8:15], v[230:237], v[44:47], v196, v196 op_sel_hi:[0,0,0]
	s_setprio 0
	s_barrier
; #define PG8_STAGE(bufoff, gbase, voff) do { _Pragma("unroll") for (int _i = 0; _i < 2; ++_i) \
;         __builtin_amdgcn_global_load_lds((const unsigned*)((const char*)(gbase) + (voff)[_i]), (LAS unsigned*)(lds + (bufoff) + ldsw + _i * 8192), 16, 0, 0); } while (0)
; #define PG8_LDA(dst, b, h) do { _Pragma("unroll") for (int m = 0; m < 4; ++m) _Pragma("unroll") for (int k = 0; k < 2; ++k) dst[m][k] = *(const LAS bf16x8*)(lds + PG8_SA(b, h) + aoffk[k] + m * 2048); } while (0)
; #define PG8_LDB(dst, b, h) do { _Pragma("unroll") for (int n = 0; n < 2; ++n) _Pragma("unroll") for (int k = 0; k < 2; ++k) dst[n][k] = *(const LAS bf16x8*)(lds + PG8_SB(b, h) + boffk[k] + n * 2048); } while (0)
; #define PG8_WAIT_V(n) asm volatile("s_waitcnt vmcnt(" #n ")" ::: "memory")
; #define PG8_WAIT_L(n) asm volatile("s_waitcnt lgkmcnt(" #n ")" ::: "memory")
; #define PG8_BAR __builtin_amdgcn_s_barrier()
; #define PG8_SCHED __builtin_amdgcn_sched_barrier(0)
; template <class Epi, class Sched, class GemmT>
; __device__ __forceinline__ void gemm_phase(LAS unsigned char* lds, const GemmT& g, const Sched& S, const Epi& E, const int wid) {
;     ...
;                 PG8_LDB(B0, 1, 0); PG8_LDB(B1, 1, 1); PG8_SCHED; PG8_LDA(At, 1, 0); PG8_STAGE(PG8_SA(0, 1), a2 + hA2, vA2);
;                 PG8_WAIT_V(8); PG8_WAIT_L(0); PG8_BAR; PG8_MMA(0, 0, At, B0); PG8_MMA(0, 1, At, B1); PG8_BAR; PG8_SCHED;
;                 PG8_LDA(At, 1, 1); PG8_STAGE(PG8_SB(1, 0), b3, vB2); PG8_STAGE(PG8_SB(1, 1), b3 + hB2, vB2); PG8_STAGE(PG8_SA(1, 0), a3, vA2);
;                 PG8_WAIT_V(8); PG8_WAIT_L(0); PG8_BAR; PG8_MMA(1, 0, At, B0); PG8_MMA(1, 1, At, B1); PG8_BAR; PG8_SCHED;
;             }
	s_add_i32 s41, 0, 0x18000
	s_add_i32 s48, 0, 0x1c000
	v_add_u32_e32 v16, s48, v184
	v_add_u32_e32 v20, s48, v185
	ds_read_b128 v[0:3], v238
	ds_read_b128 v[4:7], v239
	ds_read_b128 v[8:11], v197
	ds_read_b128 v[12:15], v198
	ds_read_b128 v[16:19], v16
	ds_read_b128 v[20:23], v20
	ds_read_b128 v[24:27], v199
	ds_read_b128 v[28:31], v200
	s_add_u32 s50, s82, 0x80000
	s_addc_u32 s51, s83, 0
	s_mov_b32 m0, s15
	ds_read_b128 v[204:207], v194 offset:32768
	ds_read_b128 v[212:215], v194 offset:34816
	ds_read_b128 v[208:211], v195 offset:32768
	ds_read_b128 v[216:219], v195 offset:34816
	ds_read_b128 v[220:223], v194 offset:36864
	ds_read_b128 v[230:233], v194 offset:38912
	ds_read_b128 v[224:227], v195 offset:36864
	ds_read_b128 v[234:237], v195 offset:38912
	global_load_lds_dwordx4 v160, s[50:51]
	s_mov_b32 m0, s21
	s_nop 0
	global_load_lds_dwordx4 v164, s[50:51]
	s_waitcnt vmcnt(8)
	s_waitcnt lgkmcnt(0)
	s_waitcnt lgkmcnt(0)
	v_mfma_scale_f32_16x16x128_f8f6f4 v[156:159], v[0:7], v[204:211], v[156:159], v196, v196 op_sel_hi:[0,0,0]
	v_mfma_scale_f32_16x16x128_f8f6f4 v[152:155], v[8:15], v[204:211], v[152:155], v196, v196 op_sel_hi:[0,0,0]
	s_barrier
	s_setprio 3
	v_mfma_scale_f32_16x16x128_f8f6f4 v[136:139], v[8:15], v[212:219], v[136:139], v196, v196 op_sel_hi:[0,0,0]
	v_mfma_scale_f32_16x16x128_f8f6f4 v[140:143], v[0:7], v[212:219], v[140:143], v196, v196 op_sel_hi:[0,0,0]
	v_mfma_scale_f32_16x16x128_f8f6f4 v[124:127], v[0:7], v[220:227], v[124:127], v196, v196 op_sel_hi:[0,0,0]
	v_mfma_scale_f32_16x16x128_f8f6f4 v[120:123], v[8:15], v[220:227], v[120:123], v196, v196 op_sel_hi:[0,0,0]
	v_mfma_scale_f32_16x16x128_f8f6f4 v[104:107], v[8:15], v[230:237], v[104:107], v196, v196 op_sel_hi:[0,0,0]
	v_mfma_scale_f32_16x16x128_f8f6f4 v[108:111], v[0:7], v[230:237], v[108:111], v196, v196 op_sel_hi:[0,0,0]
	s_setprio 0
	s_setprio 3
	v_mfma_scale_f32_16x16x128_f8f6f4 v[148:151], v[16:23], v[204:211], v[148:151], v196, v196 op_sel_hi:[0,0,0]
	v_mfma_scale_f32_16x16x128_f8f6f4 v[144:147], v[24:31], v[204:211], v[144:147], v196, v196 op_sel_hi:[0,0,0]
	v_mfma_scale_f32_16x16x128_f8f6f4 v[128:131], v[24:31], v[212:219], v[128:131], v196, v196 op_sel_hi:[0,0,0]
	v_mfma_scale_f32_16x16x128_f8f6f4 v[132:135], v[16:23], v[212:219], v[132:135], v196, v196 op_sel_hi:[0,0,0]
	v_mfma_scale_f32_16x16x128_f8f6f4 v[116:119], v[16:23], v[220:227], v[116:119], v196, v196 op_sel_hi:[0,0,0]
	v_mfma_scale_f32_16x16x128_f8f6f4 v[112:115], v[24:31], v[220:227], v[112:115], v196, v196 op_sel_hi:[0,0,0]
	v_mfma_scale_f32_16x16x128_f8f6f4 v[96:99], v[24:31], v[230:237], v[96:99], v196, v196 op_sel_hi:[0,0,0]
	v_mfma_scale_f32_16x16x128_f8f6f4 v[100:103], v[16:23], v[230:237], v[100:103], v196, v196 op_sel_hi:[0,0,0]
	s_setprio 0
	s_barrier
	s_add_i32 s41, s41, s68
	s_mov_b32 m0, s41
	ds_read_b128 v[204:207], v194 offset:49152
	ds_read_b128 v[212:215], v194 offset:51200
	ds_read_b128 v[208:211], v195 offset:49152
	ds_read_b128 v[216:219], v195 offset:51200
	ds_read_b128 v[220:223], v194 offset:53248
	ds_read_b128 v[230:233], v194 offset:55296
	ds_read_b128 v[224:227], v195 offset:53248
	ds_read_b128 v[234:237], v195 offset:55296
	s_add_u32 s98, s58, 0x80
	s_addc_u32 s99, s59, 0
	s_nop 0
	global_load_lds_dwordx4 v162, s[98:99]
	s_add_i32 m0, s41, 0x2000
	s_add_u32 s50, s58, 0x80080
	s_addc_u32 s51, s59, 0
	s_add_i32 s41, s48, s68
	global_load_lds_dwordx4 v166, s[98:99]
	s_mov_b32 m0, s41
	s_nop 0
	global_load_lds_dwordx4 v162, s[50:51]
	s_add_i32 m0, s41, 0x2000
	s_nop 0
	global_load_lds_dwordx4 v166, s[50:51]
	s_mov_b32 m0, s35
	s_nop 0
	s_add_u32 s98, s82, 0x80
	s_addc_u32 s99, s83, 0
	s_nop 0
	global_load_lds_dwordx4 v160, s[98:99]
	s_mov_b32 m0, s53
	s_nop 0
	global_load_lds_dwordx4 v164, s[98:99]
	s_waitcnt vmcnt(8)
	s_waitcnt lgkmcnt(0)
	s_waitcnt lgkmcnt(0)
	v_mfma_scale_f32_16x16x128_f8f6f4 v[84:87], v[0:7], v[204:211], v[84:87], v196, v196 op_sel_hi:[0,0,0]
	v_mfma_scale_f32_16x16x128_f8f6f4 v[80:83], v[8:15], v[204:211], v[80:83], v196, v196 op_sel_hi:[0,0,0]
	s_barrier
	s_setprio 3
	v_mfma_scale_f32_16x16x128_f8f6f4 v[64:67], v[8:15], v[212:219], v[64:67], v196, v196 op_sel_hi:[0,0,0]
	v_mfma_scale_f32_16x16x128_f8f6f4 v[68:71], v[0:7], v[212:219], v[68:71], v196, v196 op_sel_hi:[0,0,0]
	v_mfma_scale_f32_16x16x128_f8f6f4 v[52:55], v[0:7], v[220:227], v[52:55], v196, v196 op_sel_hi:[0,0,0]
	v_mfma_scale_f32_16x16x128_f8f6f4 v[48:51], v[8:15], v[220:227], v[48:51], v196, v196 op_sel_hi:[0,0,0]
	v_mfma_scale_f32_16x16x128_f8f6f4 v[32:35], v[8:15], v[230:237], v[32:35], v196, v196 op_sel_hi:[0,0,0]
	v_mfma_scale_f32_16x16x128_f8f6f4 v[36:39], v[0:7], v[230:237], v[36:39], v196, v196 op_sel_hi:[0,0,0]
	s_setprio 0
	s_setprio 3
	v_mfma_scale_f32_16x16x128_f8f6f4 v[92:95], v[16:23], v[204:211], v[92:95], v196, v196 op_sel_hi:[0,0,0]
	v_mfma_scale_f32_16x16x128_f8f6f4 v[88:91], v[24:31], v[204:211], v[88:91], v196, v196 op_sel_hi:[0,0,0]
	v_mfma_scale_f32_16x16x128_f8f6f4 v[72:75], v[24:31], v[212:219], v[72:75], v196, v196 op_sel_hi:[0,0,0]
	v_mfma_scale_f32_16x16x128_f8f6f4 v[76:79], v[16:23], v[212:219], v[76:79], v196, v196 op_sel_hi:[0,0,0]
	v_mfma_scale_f32_16x16x128_f8f6f4 v[60:63], v[16:23], v[220:227], v[60:63], v196, v196 op_sel_hi:[0,0,0]
	v_mfma_scale_f32_16x16x128_f8f6f4 v[56:59], v[24:31], v[220:227], v[56:59], v196, v196 op_sel_hi:[0,0,0]
	v_mfma_scale_f32_16x16x128_f8f6f4 v[40:43], v[24:31], v[230:237], v[40:43], v196, v196 op_sel_hi:[0,0,0]
	v_mfma_scale_f32_16x16x128_f8f6f4 v[44:47], v[16:23], v[230:237], v[44:47], v196, v196 op_sel_hi:[0,0,0]
	s_setprio 0
	s_add_i32 s40, s40, 2
	s_add_u32 s56, s56, 0x100
	s_addc_u32 s57, s57, 0
	s_add_u32 s38, s38, 0x100
	s_addc_u32 s39, s39, 0
	s_cmp_gt_u32 s40, 29
	s_barrier
	s_cbranch_scc0 .LBB0_361
	s_and_b64 vcc, exec, s[16:17]
	s_cbranch_vccz .LBB0_364
	s_barrier

; #define PG8_STAGE(bufoff, gbase, voff) do { _Pragma("unroll") for (int _i = 0; _i < 2; ++_i) \
;         __builtin_amdgcn_global_load_lds((const unsigned*)((const char*)(gbase) + (voff)[_i]), (LAS unsigned*)(lds + (bufoff) + ldsw + _i * 8192), 16, 0, 0); } while (0)
; #define PG8_LDA(dst, b, h) do { _Pragma("unroll") for (int m = 0; m < 4; ++m) _Pragma("unroll") for (int k = 0; k < 2; ++k) dst[m][k] = *(const LAS bf16x8*)(lds + PG8_SA(b, h) + aoffk[k] + m * 2048); } while (0)
; #define PG8_LDB(dst, b, h) do { _Pragma("unroll") for (int n = 0; n < 2; ++n) _Pragma("unroll") for (int k = 0; k < 2; ++k) dst[n][k] = *(const LAS bf16x8*)(lds + PG8_SB(b, h) + boffk[k] + n * 2048); } while (0)
; #define PG8_WAIT_V(n) asm volatile("s_waitcnt vmcnt(" #n ")" ::: "memory")
; #define PG8_WAIT_L(n) asm volatile("s_waitcnt lgkmcnt(" #n ")" ::: "memory")
; #define PG8_BAR __builtin_amdgcn_s_barrier()
; #define PG8_SCHED __builtin_amdgcn_sched_barrier(0)
; template <class Epi, class Sched, class GemmT>
; __device__ __forceinline__ void gemm_phase(LAS unsigned char* lds, const GemmT& g, const Sched& S, const Epi& E, const int wid) {
;     ...
;                 PG8_LDB(B0, 0, 0); PG8_LDB(B1, 0, 1); PG8_SCHED; PG8_LDA(At, 0, 0); PG8_STAGE(PG8_SA(1, 1), a1 + hstepA, voffA);
;                 PG8_WAIT_V(8); PG8_WAIT_L(0); PG8_BAR; PG8_MMA(0, 0, At, B0); PG8_MMA(0, 1, At, B1); PG8_BAR; PG8_SCHED;
;                 PG8_LDA(At, 0, 1); PG8_STAGE(PG8_SB(0, 0), b2, vB2); PG8_STAGE(PG8_SB(0, 1), b2 + hB2, vB2); PG8_STAGE(PG8_SA(0, 0), a2, vA2);
;                 PG8_WAIT_V(8); PG8_WAIT_L(0); PG8_BAR; PG8_MMA(1, 0, At, B0); PG8_MMA(1, 1, At, B1); PG8_BAR; PG8_SCHED;
.LBB0_417:
	ds_read_b128 v[140:143], v192
	ds_read_b128 v[144:147], v193
	ds_read_b128 v[148:151], v194
	ds_read_b128 v[152:155], v195
	ds_read_b128 v[156:159], v196
	ds_read_b128 v[160:163], v197
	ds_read_b128 v[164:167], v198
	ds_read_b128 v[168:171], v199
	s_add_u32 s39, s84, 0xfff00080
	s_addc_u32 s40, s85, -1
	s_cmp_eq_u32 s38, 60
	s_cselect_b32 s87, s57, s40
	s_cselect_b32 s86, s56, s39
	s_cselect_b32 s71, s16, s37
	s_cselect_b32 s70, s5, s36
	s_add_i32 m0, s9, 0xc000
	ds_read_b128 v[172:175], v200
	ds_read_b128 v[208:211], v200 offset:2048
	ds_read_b128 v[212:215], v201
	ds_read_b128 v[216:219], v201 offset:2048
	ds_read_b128 v[220:223], v200 offset:4096
	ds_read_b128 v[224:227], v200 offset:6144
	ds_read_b128 v[230:233], v201 offset:4096
	ds_read_b128 v[234:237], v201 offset:6144
	global_load_lds_dwordx4 v128, s[84:85]
	s_add_i32 m0, s9, 0xe000
	s_nop 0
	global_load_lds_dwordx4 v132, s[84:85]
	s_waitcnt vmcnt(8)
	s_waitcnt lgkmcnt(0)
	s_waitcnt lgkmcnt(0)
	v_mfma_f32_16x16x32_bf16 v[124:127], v[140:143], v[172:175], v[124:127]
	v_mfma_f32_16x16x32_bf16 v[124:127], v[144:147], v[212:215], v[124:127]
	v_mfma_f32_16x16x32_bf16 v[120:123], v[152:155], v[212:215], v[120:123]
	v_mfma_f32_16x16x32_bf16 v[120:123], v[148:151], v[172:175], v[120:123]
	s_barrier
	s_setprio 3
	v_mfma_f32_16x16x32_bf16 v[112:115], v[148:151], v[208:211], v[112:115]
	v_mfma_f32_16x16x32_bf16 v[112:115], v[152:155], v[216:219], v[112:115]
	v_mfma_f32_16x16x32_bf16 v[116:119], v[144:147], v[216:219], v[116:119]
	v_mfma_f32_16x16x32_bf16 v[116:119], v[140:143], v[208:211], v[116:119]
	v_mfma_f32_16x16x32_bf16 v[100:103], v[140:143], v[220:223], v[100:103]
	v_mfma_f32_16x16x32_bf16 v[100:103], v[144:147], v[230:233], v[100:103]
	v_mfma_f32_16x16x32_bf16 v[96:99], v[152:155], v[230:233], v[96:99]
	v_mfma_f32_16x16x32_bf16 v[96:99], v[148:151], v[220:223], v[96:99]
	v_mfma_f32_16x16x32_bf16 v[76:79], v[148:151], v[224:227], v[76:79]
	v_mfma_f32_16x16x32_bf16 v[76:79], v[152:155], v[234:237], v[76:79]
	v_mfma_f32_16x16x32_bf16 v[84:87], v[144:147], v[234:237], v[84:87]
	v_mfma_f32_16x16x32_bf16 v[84:87], v[140:143], v[224:227], v[84:87]
	s_setprio 0
	s_setprio 3
	v_mfma_f32_16x16x32_bf16 v[108:111], v[156:159], v[172:175], v[108:111]
	v_mfma_f32_16x16x32_bf16 v[108:111], v[160:163], v[212:215], v[108:111]
	v_mfma_f32_16x16x32_bf16 v[104:107], v[168:171], v[212:215], v[104:107]
	v_mfma_f32_16x16x32_bf16 v[104:107], v[164:167], v[172:175], v[104:107]
	v_mfma_f32_16x16x32_bf16 v[88:91], v[164:167], v[208:211], v[88:91]
	v_mfma_f32_16x16x32_bf16 v[88:91], v[168:171], v[216:219], v[88:91]
	v_mfma_f32_16x16x32_bf16 v[92:95], v[160:163], v[216:219], v[92:95]
	v_mfma_f32_16x16x32_bf16 v[92:95], v[156:159], v[208:211], v[92:95]
	v_mfma_f32_16x16x32_bf16 v[68:71], v[156:159], v[220:223], v[68:71]
	v_mfma_f32_16x16x32_bf16 v[68:71], v[160:163], v[230:233], v[68:71]
	v_mfma_f32_16x16x32_bf16 v[64:67], v[168:171], v[230:233], v[64:67]
	v_mfma_f32_16x16x32_bf16 v[64:67], v[164:167], v[220:223], v[64:67]
	v_mfma_f32_16x16x32_bf16 v[40:43], v[164:167], v[224:227], v[40:43]
	v_mfma_f32_16x16x32_bf16 v[40:43], v[168:171], v[234:237], v[40:43]
	v_mfma_f32_16x16x32_bf16 v[48:51], v[160:163], v[234:237], v[48:51]
	v_mfma_f32_16x16x32_bf16 v[48:51], v[156:159], v[224:227], v[48:51]
	s_setprio 0
	s_barrier
	s_add_i32 s39, s35, s68
	s_mov_b32 m0, s39
	ds_read_b128 v[172:175], v200 offset:16384
	ds_read_b128 v[208:211], v200 offset:18432
	ds_read_b128 v[212:215], v201 offset:16384
	ds_read_b128 v[216:219], v201 offset:18432
	ds_read_b128 v[220:223], v200 offset:20480
	ds_read_b128 v[224:227], v200 offset:22528
	ds_read_b128 v[230:233], v201 offset:20480
	ds_read_b128 v[234:237], v201 offset:22528
	global_load_lds_dwordx4 v130, s[70:71]
	s_add_i32 m0, s39, 0x2000
	s_add_u32 s40, s70, 0x100000
	s_addc_u32 s41, s71, 0
	s_add_i32 s39, s69, s68
	global_load_lds_dwordx4 v134, s[70:71]
	s_mov_b32 m0, s39
	s_nop 0
	global_load_lds_dwordx4 v130, s[40:41]
	s_add_i32 m0, s39, 0x2000
	s_nop 0
	global_load_lds_dwordx4 v134, s[40:41]
	s_mov_b32 m0, s9
	s_nop 0
	global_load_lds_dwordx4 v128, s[86:87]
	s_mov_b32 m0, s29
	s_nop 0
	global_load_lds_dwordx4 v132, s[86:87]
	s_waitcnt vmcnt(8)
	s_waitcnt lgkmcnt(0)
	s_waitcnt lgkmcnt(0)
	v_mfma_f32_16x16x32_bf16 v[28:31], v[140:143], v[172:175], v[28:31]
	v_mfma_f32_16x16x32_bf16 v[28:31], v[144:147], v[212:215], v[28:31]
	v_mfma_f32_16x16x32_bf16 v[24:27], v[152:155], v[212:215], v[24:27]
	v_mfma_f32_16x16x32_bf16 v[24:27], v[148:151], v[172:175], v[24:27]
	s_barrier
	s_setprio 3
	v_mfma_f32_16x16x32_bf16 v[16:19], v[148:151], v[208:211], v[16:19]
	v_mfma_f32_16x16x32_bf16 v[16:19], v[152:155], v[216:219], v[16:19]
	v_mfma_f32_16x16x32_bf16 v[20:23], v[144:147], v[216:219], v[20:23]
	v_mfma_f32_16x16x32_bf16 v[20:23], v[140:143], v[208:211], v[20:23]
	v_mfma_f32_16x16x32_bf16 v[12:15], v[140:143], v[220:223], v[12:15]
	v_mfma_f32_16x16x32_bf16 v[12:15], v[144:147], v[230:233], v[12:15]
	v_mfma_f32_16x16x32_bf16 v[8:11], v[152:155], v[230:233], v[8:11]
	v_mfma_f32_16x16x32_bf16 v[8:11], v[148:151], v[220:223], v[8:11]
	v_mfma_f32_16x16x32_bf16 v[0:3], v[148:151], v[224:227], v[0:3]
	v_mfma_f32_16x16x32_bf16 v[0:3], v[152:155], v[234:237], v[0:3]
	v_mfma_f32_16x16x32_bf16 v[4:7], v[144:147], v[234:237], v[4:7]
	v_mfma_f32_16x16x32_bf16 v[4:7], v[140:143], v[224:227], v[4:7]
	s_setprio 0
	s_setprio 3
	v_mfma_f32_16x16x32_bf16 v[80:83], v[156:159], v[172:175], v[80:83]
	v_mfma_f32_16x16x32_bf16 v[80:83], v[160:163], v[212:215], v[80:83]
	v_mfma_f32_16x16x32_bf16 v[72:75], v[168:171], v[212:215], v[72:75]
	v_mfma_f32_16x16x32_bf16 v[72:75], v[164:167], v[172:175], v[72:75]
	v_mfma_f32_16x16x32_bf16 v[56:59], v[164:167], v[208:211], v[56:59]
	v_mfma_f32_16x16x32_bf16 v[56:59], v[168:171], v[216:219], v[56:59]
	v_mfma_f32_16x16x32_bf16 v[60:63], v[160:163], v[216:219], v[60:63]
	v_mfma_f32_16x16x32_bf16 v[60:63], v[156:159], v[208:211], v[60:63]
	v_mfma_f32_16x16x32_bf16 v[52:55], v[156:159], v[220:223], v[52:55]
	v_mfma_f32_16x16x32_bf16 v[52:55], v[160:163], v[230:233], v[52:55]
	v_mfma_f32_16x16x32_bf16 v[44:47], v[168:171], v[230:233], v[44:47]
	v_mfma_f32_16x16x32_bf16 v[44:47], v[164:167], v[220:223], v[44:47]
	v_mfma_f32_16x16x32_bf16 v[32:35], v[164:167], v[224:227], v[32:35]
	v_mfma_f32_16x16x32_bf16 v[32:35], v[168:171], v[234:237], v[32:35]
	v_mfma_f32_16x16x32_bf16 v[36:39], v[160:163], v[234:237], v[36:39]
	v_mfma_f32_16x16x32_bf16 v[36:39], v[156:159], v[224:227], v[36:39]
	s_setprio 0
	s_barrier
; #define PG8_STAGE(bufoff, gbase, voff) do { _Pragma("unroll") for (int _i = 0; _i < 2; ++_i) \
;         __builtin_amdgcn_global_load_lds((const unsigned*)((const char*)(gbase) + (voff)[_i]), (LAS unsigned*)(lds + (bufoff) + ldsw + _i * 8192), 16, 0, 0); } while (0)
; #define PG8_LDA(dst, b, h) do { _Pragma("unroll") for (int m = 0; m < 4; ++m) _Pragma("unroll") for (int k = 0; k < 2; ++k) dst[m][k] = *(const LAS bf16x8*)(lds + PG8_SA(b, h) + aoffk[k] + m * 2048); } while (0)
; #define PG8_LDB(dst, b, h) do { _Pragma("unroll") for (int n = 0; n < 2; ++n) _Pragma("unroll") for (int k = 0; k < 2; ++k) dst[n][k] = *(const LAS bf16x8*)(lds + PG8_SB(b, h) + boffk[k] + n * 2048); } while (0)
; #define PG8_WAIT_V(n) asm volatile("s_waitcnt vmcnt(" #n ")" ::: "memory")
; #define PG8_WAIT_L(n) asm volatile("s_waitcnt lgkmcnt(" #n ")" ::: "memory")
; #define PG8_BAR __builtin_amdgcn_s_barrier()
; #define PG8_SCHED __builtin_amdgcn_sched_barrier(0)
; template <class Epi, class Sched, class GemmT>
; __device__ __forceinline__ void gemm_phase(LAS unsigned char* lds, const GemmT& g, const Sched& S, const Epi& E, const int wid) {
;     ...
;                 PG8_LDB(B0, 1, 0); PG8_LDB(B1, 1, 1); PG8_SCHED; PG8_LDA(At, 1, 0); PG8_STAGE(PG8_SA(0, 1), a2 + hA2, vA2);
;                 PG8_WAIT_V(8); PG8_WAIT_L(0); PG8_BAR; PG8_MMA(0, 0, At, B0); PG8_MMA(0, 1, At, B1); PG8_BAR; PG8_SCHED;
;                 PG8_LDA(At, 1, 1); PG8_STAGE(PG8_SB(1, 0), b3, vB2); PG8_STAGE(PG8_SB(1, 1), b3 + hB2, vB2); PG8_STAGE(PG8_SA(1, 0), a3, vA2);
;                 PG8_WAIT_V(8); PG8_WAIT_L(0); PG8_BAR; PG8_MMA(1, 0, At, B0); PG8_MMA(1, 1, At, B1); PG8_BAR; PG8_SCHED;
;             }
	s_add_i32 s39, 0, 0x18000
	s_add_i32 s48, 0, 0x1c000
	ds_read_b128 v[140:143], v176
	ds_read_b128 v[144:147], v177
	ds_read_b128 v[148:151], v202
	ds_read_b128 v[152:155], v203
	ds_read_b128 v[156:159], v180
	ds_read_b128 v[160:163], v181
	ds_read_b128 v[164:167], v204
	ds_read_b128 v[168:171], v205
	s_add_u32 s40, s86, 0x100000
	s_addc_u32 s41, s87, 0
	s_mov_b32 m0, s93
	ds_read_b128 v[172:175], v200 offset:32768
	ds_read_b128 v[208:211], v200 offset:34816
	ds_read_b128 v[212:215], v201 offset:32768
	ds_read_b128 v[216:219], v201 offset:34816
	ds_read_b128 v[220:223], v200 offset:36864
	ds_read_b128 v[224:227], v200 offset:38912
	ds_read_b128 v[230:233], v201 offset:36864
	ds_read_b128 v[234:237], v201 offset:38912
	global_load_lds_dwordx4 v128, s[40:41]
	s_mov_b32 m0, s6
	s_nop 0
	global_load_lds_dwordx4 v132, s[40:41]
	s_waitcnt vmcnt(8)
	s_waitcnt lgkmcnt(0)
	s_waitcnt lgkmcnt(0)
	v_mfma_f32_16x16x32_bf16 v[124:127], v[140:143], v[172:175], v[124:127]
	v_mfma_f32_16x16x32_bf16 v[124:127], v[144:147], v[212:215], v[124:127]
	v_mfma_f32_16x16x32_bf16 v[120:123], v[152:155], v[212:215], v[120:123]
	v_mfma_f32_16x16x32_bf16 v[120:123], v[148:151], v[172:175], v[120:123]
	s_barrier
	s_setprio 3
	v_mfma_f32_16x16x32_bf16 v[112:115], v[148:151], v[208:211], v[112:115]
	v_mfma_f32_16x16x32_bf16 v[112:115], v[152:155], v[216:219], v[112:115]
	v_mfma_f32_16x16x32_bf16 v[116:119], v[144:147], v[216:219], v[116:119]
	v_mfma_f32_16x16x32_bf16 v[116:119], v[140:143], v[208:211], v[116:119]
	v_mfma_f32_16x16x32_bf16 v[100:103], v[140:143], v[220:223], v[100:103]
	v_mfma_f32_16x16x32_bf16 v[100:103], v[144:147], v[230:233], v[100:103]
	v_mfma_f32_16x16x32_bf16 v[96:99], v[152:155], v[230:233], v[96:99]
	v_mfma_f32_16x16x32_bf16 v[96:99], v[148:151], v[220:223], v[96:99]
	v_mfma_f32_16x16x32_bf16 v[76:79], v[148:151], v[224:227], v[76:79]
	v_mfma_f32_16x16x32_bf16 v[76:79], v[152:155], v[234:237], v[76:79]
	v_mfma_f32_16x16x32_bf16 v[84:87], v[144:147], v[234:237], v[84:87]
	v_mfma_f32_16x16x32_bf16 v[84:87], v[140:143], v[224:227], v[84:87]
	s_setprio 0
	s_setprio 3
	v_mfma_f32_16x16x32_bf16 v[108:111], v[156:159], v[172:175], v[108:111]
	v_mfma_f32_16x16x32_bf16 v[108:111], v[160:163], v[212:215], v[108:111]
	v_mfma_f32_16x16x32_bf16 v[104:107], v[168:171], v[212:215], v[104:107]
	v_mfma_f32_16x16x32_bf16 v[104:107], v[164:167], v[172:175], v[104:107]
	v_mfma_f32_16x16x32_bf16 v[88:91], v[164:167], v[208:211], v[88:91]
	v_mfma_f32_16x16x32_bf16 v[88:91], v[168:171], v[216:219], v[88:91]
	v_mfma_f32_16x16x32_bf16 v[92:95], v[160:163], v[216:219], v[92:95]
	v_mfma_f32_16x16x32_bf16 v[92:95], v[156:159], v[208:211], v[92:95]
	v_mfma_f32_16x16x32_bf16 v[68:71], v[156:159], v[220:223], v[68:71]
	v_mfma_f32_16x16x32_bf16 v[68:71], v[160:163], v[230:233], v[68:71]
	v_mfma_f32_16x16x32_bf16 v[64:67], v[168:171], v[230:233], v[64:67]
	v_mfma_f32_16x16x32_bf16 v[64:67], v[164:167], v[220:223], v[64:67]
	v_mfma_f32_16x16x32_bf16 v[40:43], v[164:167], v[224:227], v[40:43]
	v_mfma_f32_16x16x32_bf16 v[40:43], v[168:171], v[234:237], v[40:43]
	v_mfma_f32_16x16x32_bf16 v[48:51], v[160:163], v[234:237], v[48:51]
	v_mfma_f32_16x16x32_bf16 v[48:51], v[156:159], v[224:227], v[48:51]
	s_setprio 0
	s_barrier
	s_add_i32 s39, s39, s68
	s_mov_b32 m0, s39
	ds_read_b128 v[172:175], v200 offset:49152
	ds_read_b128 v[208:211], v200 offset:51200
	ds_read_b128 v[212:215], v201 offset:49152
	ds_read_b128 v[216:219], v201 offset:51200
	ds_read_b128 v[220:223], v200 offset:53248
	ds_read_b128 v[224:227], v200 offset:55296
	ds_read_b128 v[230:233], v201 offset:53248
	ds_read_b128 v[234:237], v201 offset:55296
	s_add_u32 s98, s70, 0x80
	s_addc_u32 s99, s71, 0
	s_nop 0
	global_load_lds_dwordx4 v130, s[98:99]
	s_add_i32 m0, s39, 0x2000
	s_add_u32 s40, s70, 0x100080
	s_addc_u32 s41, s71, 0
	s_add_i32 s39, s48, s68
	global_load_lds_dwordx4 v134, s[98:99]
	s_mov_b32 m0, s39
	s_nop 0
	global_load_lds_dwordx4 v130, s[40:41]
	s_add_i32 m0, s39, 0x2000
	s_nop 0
	global_load_lds_dwordx4 v134, s[40:41]
	s_mov_b32 m0, s7
	s_nop 0
	s_add_u32 s98, s86, 0x80
	s_addc_u32 s99, s87, 0
	s_nop 0
	global_load_lds_dwordx4 v128, s[98:99]
	s_mov_b32 m0, s12
	s_nop 0
	global_load_lds_dwordx4 v132, s[98:99]
	s_waitcnt vmcnt(8)
	s_waitcnt lgkmcnt(0)
	s_waitcnt lgkmcnt(0)
	v_mfma_f32_16x16x32_bf16 v[28:31], v[140:143], v[172:175], v[28:31]
	v_mfma_f32_16x16x32_bf16 v[28:31], v[144:147], v[212:215], v[28:31]
	v_mfma_f32_16x16x32_bf16 v[24:27], v[152:155], v[212:215], v[24:27]
	v_mfma_f32_16x16x32_bf16 v[24:27], v[148:151], v[172:175], v[24:27]
	s_barrier
	s_setprio 3
	v_mfma_f32_16x16x32_bf16 v[16:19], v[148:151], v[208:211], v[16:19]
	v_mfma_f32_16x16x32_bf16 v[16:19], v[152:155], v[216:219], v[16:19]
	v_mfma_f32_16x16x32_bf16 v[20:23], v[144:147], v[216:219], v[20:23]
	v_mfma_f32_16x16x32_bf16 v[20:23], v[140:143], v[208:211], v[20:23]
	v_mfma_f32_16x16x32_bf16 v[12:15], v[140:143], v[220:223], v[12:15]
	v_mfma_f32_16x16x32_bf16 v[12:15], v[144:147], v[230:233], v[12:15]
	v_mfma_f32_16x16x32_bf16 v[8:11], v[152:155], v[230:233], v[8:11]
	v_mfma_f32_16x16x32_bf16 v[8:11], v[148:151], v[220:223], v[8:11]
	v_mfma_f32_16x16x32_bf16 v[0:3], v[148:151], v[224:227], v[0:3]
	v_mfma_f32_16x16x32_bf16 v[0:3], v[152:155], v[234:237], v[0:3]
	v_mfma_f32_16x16x32_bf16 v[4:7], v[144:147], v[234:237], v[4:7]
	v_mfma_f32_16x16x32_bf16 v[4:7], v[140:143], v[224:227], v[4:7]
	s_setprio 0
	s_setprio 3
	v_mfma_f32_16x16x32_bf16 v[80:83], v[156:159], v[172:175], v[80:83]
	v_mfma_f32_16x16x32_bf16 v[80:83], v[160:163], v[212:215], v[80:83]
	v_mfma_f32_16x16x32_bf16 v[72:75], v[168:171], v[212:215], v[72:75]
	v_mfma_f32_16x16x32_bf16 v[72:75], v[164:167], v[172:175], v[72:75]
	v_mfma_f32_16x16x32_bf16 v[56:59], v[164:167], v[208:211], v[56:59]
	v_mfma_f32_16x16x32_bf16 v[56:59], v[168:171], v[216:219], v[56:59]
	v_mfma_f32_16x16x32_bf16 v[60:63], v[160:163], v[216:219], v[60:63]
	v_mfma_f32_16x16x32_bf16 v[60:63], v[156:159], v[208:211], v[60:63]
	v_mfma_f32_16x16x32_bf16 v[52:55], v[156:159], v[220:223], v[52:55]
	v_mfma_f32_16x16x32_bf16 v[52:55], v[160:163], v[230:233], v[52:55]
	v_mfma_f32_16x16x32_bf16 v[44:47], v[168:171], v[230:233], v[44:47]
	v_mfma_f32_16x16x32_bf16 v[44:47], v[164:167], v[220:223], v[44:47]
	v_mfma_f32_16x16x32_bf16 v[32:35], v[164:167], v[224:227], v[32:35]
	v_mfma_f32_16x16x32_bf16 v[32:35], v[168:171], v[234:237], v[32:35]
	v_mfma_f32_16x16x32_bf16 v[36:39], v[160:163], v[234:237], v[36:39]
	v_mfma_f32_16x16x32_bf16 v[36:39], v[156:159], v[224:227], v[36:39]
	s_setprio 0
	s_add_i32 s38, s38, 2
	s_add_u32 s84, s84, 0x100
	s_addc_u32 s85, s85, 0
	s_add_u32 s36, s36, 0x100
	s_addc_u32 s37, s37, 0
	s_cmp_gt_u32 s38, 61
	s_barrier
	s_cbranch_scc0 .LBB0_417
	s_and_b64 vcc, exec, s[20:21]
	s_cbranch_vccz .LBB0_420
	s_barrier

; #define PG8_STAGE(bufoff, gbase, voff) do { _Pragma("unroll") for (int _i = 0; _i < 2; ++_i) \
;         __builtin_amdgcn_global_load_lds((const unsigned*)((const char*)(gbase) + (voff)[_i]), (LAS unsigned*)(lds + (bufoff) + ldsw + _i * 8192), 16, 0, 0); } while (0)
; #define PG8_LDA(dst, b, h) do { _Pragma("unroll") for (int m = 0; m < 4; ++m) _Pragma("unroll") for (int k = 0; k < 2; ++k) dst[m][k] = *(const LAS bf16x8*)(lds + PG8_SA(b, h) + aoffk[k] + m * 2048); } while (0)
; #define PG8_WAIT_V(n) asm volatile("s_waitcnt vmcnt(" #n ")" ::: "memory")
; #define PG8_WAIT_L(n) asm volatile("s_waitcnt lgkmcnt(" #n ")" ::: "memory")
; template <class Epi, class Sched, class GemmT>
; __device__ __forceinline__ void gemm_phase(LAS unsigned char* lds, const GemmT& g, const Sched& S, const Epi& E, const int wid) {
;     ...
;             const Seg ns = (sgi + 1 < NSEG) ? g.seg(cur, sgi + 1) : g.seg(has_next ? nxt : cur, 0);
;             unsigned nvA[2], nvB[2]; size_t nhA, nhB;
;             if constexpr (GemmT::UNIFORM) { nvA[0] = voffA[0]; nvA[1] = voffA[1]; nvB[0] = voffB[0]; nvB[1] = voffB[1]; nhA = hstepA; nhB = hstepB; }
;             else PG8_VOFFS(nvA, nvB, nhA, nhB, ns);
;             const int nt = cs.nt;
;             for (int t = 0; t < nt; t += 2) {
;                 const bool last = (t == nt - 2);
;                 const char* a1 = cA + (size_t)(t + 1) * kstep;
;                 const char* a2 = last ? ns.A : cA + (size_t)(t + 2) * kstep; const char* b2 = last ? ns.B : cB + (size_t)(t + 2) * kstep;
;                 const char* a3 = a2 + kstep; const char* b3 = b2 + kstep;
;                 unsigned vA2[2], vB2[2];
; #pragma unroll
;                 for (int i = 0; i < 2; ++i) { vA2[i] = last ? nvA[i] : voffA[i]; vB2[i] = last ? nvB[i] : voffB[i]; }
;                 const size_t hA2 = last ? nhA : hstepA, hB2 = last ? nhB : hstepB;
;                 PG8_LDB(B0, 0, 0); PG8_LDB(B1, 0, 1); PG8_SCHED; PG8_LDA(At, 0, 0); PG8_STAGE(PG8_SA(1, 1), a1 + hstepA, voffA);
;                 PG8_WAIT_V(8); PG8_WAIT_L(0); PG8_BAR; PG8_MMA(0, 0, At, B0); PG8_MMA(0, 1, At, B1); PG8_BAR; PG8_SCHED;
;                 PG8_LDA(At, 0, 1); PG8_STAGE(PG8_SB(0, 0), b2, vB2); PG8_STAGE(PG8_SB(0, 1), b2 + hB2, vB2); PG8_STAGE(PG8_SA(0, 0), a2, vA2);
;                 PG8_WAIT_V(8); PG8_WAIT_L(0); PG8_BAR; PG8_MMA(1, 0, At, B0); PG8_MMA(1, 1, At, B1); PG8_BAR; PG8_SCHED;
.LBB0_764:
	s_cmp_eq_u32 s43, s56
	s_cselect_b64 vcc, -1, 0
	s_add_i32 s90, s90, 2
	v_add_u32_e32 v131, s62, v208
	s_add_u32 s48, s50, s56
	v_add_u32_e32 v133, s62, v209
	ds_read_b128 v[144:147], v131
	ds_read_b128 v[148:151], v133
	v_add_u32_e32 v131, s63, v208
	s_addc_u32 s49, s51, s57
	v_add_u32_e32 v133, s63, v209
	ds_read_b128 v[152:155], v131
	ds_read_b128 v[156:159], v133
	v_add_u32_e32 v131, s64, v208
	s_add_u32 s58, s48, 0x100
	v_add_u32_e32 v133, s64, v209
	ds_read_b128 v[160:163], v131
	ds_read_b128 v[164:167], v133
	v_add_u32_e32 v131, s65, v208
	s_addc_u32 s59, s49, 0
	v_add_u32_e32 v133, s65, v209
	ds_read_b128 v[168:171], v131
	ds_read_b128 v[172:175], v133
	s_and_b64 s[48:49], vcc, exec
	s_cselect_b32 s59, s19, s59
	s_cselect_b32 s58, s18, s58
	s_add_u32 s60, s85, s56
	s_addc_u32 s61, s89, s57
	s_and_b64 s[48:49], vcc, exec
	v_cndmask_b32_e32 v138, v132, v190, vcc
	v_cndmask_b32_e32 v0, v143, v214, vcc
	v_cndmask_b32_e32 v140, v130, v194, vcc
	v_cndmask_b32_e32 v188, v142, v192, vcc
	s_cselect_b32 s61, s13, s61
	s_cselect_b32 s60, s12, s60
	s_cselect_b32 s91, 0, s45
	s_cselect_b32 s92, s6, s44
	v_lshl_add_u64 v[202:203], v[134:135], 0, s[56:57]
	s_add_i32 m0, s14, 0xc000
	ds_read_b128 v[176:179], v212
	ds_read_b128 v[180:183], v212 offset:2048
	ds_read_b128 v[184:187], v213
	ds_read_b128 v[216:219], v213 offset:2048
	ds_read_b128 v[220:223], v212 offset:4096
	ds_read_b128 v[224:227], v212 offset:6144
	ds_read_b128 v[230:233], v213 offset:4096
	ds_read_b128 v[234:237], v213 offset:6144
	global_load_lds_dwordx4 v[202:203], off
	v_lshl_add_u64 v[202:203], v[136:137], 0, s[56:57]
	s_add_i32 m0, s14, 0xe000
	s_nop 0
	global_load_lds_dwordx4 v[202:203], off
	s_waitcnt vmcnt(8)
	s_waitcnt lgkmcnt(0)
	s_waitcnt lgkmcnt(0)
	v_mfma_f32_16x16x32_bf16 v[126:129], v[144:147], v[176:179], v[126:129]
	v_mfma_f32_16x16x32_bf16 v[126:129], v[148:151], v[184:187], v[126:129]
	v_mfma_f32_16x16x32_bf16 v[122:125], v[156:159], v[184:187], v[122:125]
	v_mfma_f32_16x16x32_bf16 v[122:125], v[152:155], v[176:179], v[122:125]
	s_barrier
	s_setprio 3
	v_mfma_f32_16x16x32_bf16 v[106:109], v[152:155], v[180:183], v[106:109]
	v_mfma_f32_16x16x32_bf16 v[106:109], v[156:159], v[216:219], v[106:109]
	v_mfma_f32_16x16x32_bf16 v[110:113], v[148:151], v[216:219], v[110:113]
	v_mfma_f32_16x16x32_bf16 v[110:113], v[144:147], v[180:183], v[110:113]
	v_mfma_f32_16x16x32_bf16 v[94:97], v[144:147], v[220:223], v[94:97]
	v_mfma_f32_16x16x32_bf16 v[94:97], v[148:151], v[230:233], v[94:97]
	v_mfma_f32_16x16x32_bf16 v[90:93], v[156:159], v[230:233], v[90:93]
	v_mfma_f32_16x16x32_bf16 v[90:93], v[152:155], v[220:223], v[90:93]
	v_mfma_f32_16x16x32_bf16 v[74:77], v[152:155], v[224:227], v[74:77]
	v_mfma_f32_16x16x32_bf16 v[74:77], v[156:159], v[234:237], v[74:77]
	v_mfma_f32_16x16x32_bf16 v[78:81], v[148:151], v[234:237], v[78:81]
	v_mfma_f32_16x16x32_bf16 v[78:81], v[144:147], v[224:227], v[78:81]
	s_setprio 0
	s_setprio 3
	v_mfma_f32_16x16x32_bf16 v[118:121], v[160:163], v[176:179], v[118:121]
	v_mfma_f32_16x16x32_bf16 v[118:121], v[164:167], v[184:187], v[118:121]
	v_mfma_f32_16x16x32_bf16 v[114:117], v[172:175], v[184:187], v[114:117]
	v_mfma_f32_16x16x32_bf16 v[114:117], v[168:171], v[176:179], v[114:117]
	v_mfma_f32_16x16x32_bf16 v[98:101], v[168:171], v[180:183], v[98:101]
	v_mfma_f32_16x16x32_bf16 v[98:101], v[172:175], v[216:219], v[98:101]
	v_mfma_f32_16x16x32_bf16 v[102:105], v[164:167], v[216:219], v[102:105]
	v_mfma_f32_16x16x32_bf16 v[102:105], v[160:163], v[180:183], v[102:105]
	v_mfma_f32_16x16x32_bf16 v[86:89], v[160:163], v[220:223], v[86:89]
	v_mfma_f32_16x16x32_bf16 v[86:89], v[164:167], v[230:233], v[86:89]
	v_mfma_f32_16x16x32_bf16 v[82:85], v[172:175], v[230:233], v[82:85]
	v_mfma_f32_16x16x32_bf16 v[82:85], v[168:171], v[220:223], v[82:85]
	v_mfma_f32_16x16x32_bf16 v[66:69], v[168:171], v[224:227], v[66:69]
	v_mfma_f32_16x16x32_bf16 v[66:69], v[172:175], v[234:237], v[66:69]
	v_mfma_f32_16x16x32_bf16 v[70:73], v[164:167], v[234:237], v[70:73]
	v_mfma_f32_16x16x32_bf16 v[70:73], v[160:163], v[224:227], v[70:73]
	s_setprio 0
	s_barrier
	s_add_i32 s48, s62, s68
	s_mov_b32 m0, s48
	ds_read_b128 v[176:179], v212 offset:16384
	ds_read_b128 v[180:183], v213 offset:16384
	ds_read_b128 v[184:187], v212 offset:18432
	ds_read_b128 v[216:219], v213 offset:18432
	ds_read_b128 v[220:223], v212 offset:20480
	ds_read_b128 v[224:227], v213 offset:20480
	ds_read_b128 v[230:233], v212 offset:22528
	ds_read_b128 v[234:237], v213 offset:22528
	global_load_lds_dwordx4 v0, s[60:61]
	s_add_i32 m0, s48, 0x2000
	v_mov_b32_e32 v189, v1
	s_add_u32 s48, s60, s92
	v_lshl_add_u64 v[202:203], s[60:61], 0, v[0:1]
	v_lshl_add_u64 v[238:239], s[60:61], 0, v[188:189]
	global_load_lds_dwordx4 v188, s[60:61]
	s_addc_u32 s49, s61, s91
	s_add_i32 s60, s64, s68
	s_mov_b32 m0, s60
	v_mov_b32_e32 v139, v1
	global_load_lds_dwordx4 v0, s[48:49]
	s_add_i32 m0, s60, 0x2000
	v_mov_b32_e32 v141, v1
	global_load_lds_dwordx4 v188, s[48:49]
	s_mov_b32 m0, s14
	v_lshl_add_u64 v[240:241], s[48:49], 0, v[0:1]
	global_load_lds_dwordx4 v138, s[58:59]
	s_mov_b32 m0, s15
	v_lshl_add_u64 v[242:243], s[48:49], 0, v[188:189]
	global_load_lds_dwordx4 v140, s[58:59]
	s_waitcnt vmcnt(8)
	s_waitcnt lgkmcnt(0)
	v_lshl_add_u64 v[188:189], s[58:59], 0, v[138:139]
	v_lshl_add_u64 v[244:245], s[58:59], 0, v[140:141]
	s_waitcnt lgkmcnt(0)
	v_mfma_f32_16x16x32_bf16 v[62:65], v[144:147], v[176:179], v[62:65]
	v_mfma_f32_16x16x32_bf16 v[62:65], v[148:151], v[180:183], v[62:65]
	v_mfma_f32_16x16x32_bf16 v[58:61], v[156:159], v[180:183], v[58:61]
	v_mfma_f32_16x16x32_bf16 v[58:61], v[152:155], v[176:179], v[58:61]
	s_barrier
; #define PG8_STAGE(bufoff, gbase, voff) do { _Pragma("unroll") for (int _i = 0; _i < 2; ++_i) \
;         __builtin_amdgcn_global_load_lds((const unsigned*)((const char*)(gbase) + (voff)[_i]), (LAS unsigned*)(lds + (bufoff) + ldsw + _i * 8192), 16, 0, 0); } while (0)
; #define PG8_LDA(dst, b, h) do { _Pragma("unroll") for (int m = 0; m < 4; ++m) _Pragma("unroll") for (int k = 0; k < 2; ++k) dst[m][k] = *(const LAS bf16x8*)(lds + PG8_SA(b, h) + aoffk[k] + m * 2048); } while (0)
; #define PG8_LDB(dst, b, h) do { _Pragma("unroll") for (int n = 0; n < 2; ++n) _Pragma("unroll") for (int k = 0; k < 2; ++k) dst[n][k] = *(const LAS bf16x8*)(lds + PG8_SB(b, h) + boffk[k] + n * 2048); } while (0)
; #define PG8_WAIT_V(n) asm volatile("s_waitcnt vmcnt(" #n ")" ::: "memory")
; #define PG8_WAIT_L(n) asm volatile("s_waitcnt lgkmcnt(" #n ")" ::: "memory")
; #define PG8_BAR __builtin_amdgcn_s_barrier()
; #define PG8_SCHED __builtin_amdgcn_sched_barrier(0)
; template <class Epi, class Sched, class GemmT>
; __device__ __forceinline__ void gemm_phase(LAS unsigned char* lds, const GemmT& g, const Sched& S, const Epi& E, const int wid) {
;     ...
;                 PG8_WAIT_V(8); PG8_WAIT_L(0); PG8_BAR; PG8_MMA(0, 0, At, B0); PG8_MMA(0, 1, At, B1); PG8_BAR; PG8_SCHED;
;                 PG8_LDA(At, 0, 1); PG8_STAGE(PG8_SB(0, 0), b2, vB2); PG8_STAGE(PG8_SB(0, 1), b2 + hB2, vB2); PG8_STAGE(PG8_SA(0, 0), a2, vA2);
;                 PG8_WAIT_V(8); PG8_WAIT_L(0); PG8_BAR; PG8_MMA(1, 0, At, B0); PG8_MMA(1, 1, At, B1); PG8_BAR; PG8_SCHED;
;                 PG8_LDB(B0, 1, 0); PG8_LDB(B1, 1, 1); PG8_SCHED; PG8_LDA(At, 1, 0); PG8_STAGE(PG8_SA(0, 1), a2 + hA2, vA2);
;                 PG8_WAIT_V(8); PG8_WAIT_L(0); PG8_BAR; PG8_MMA(0, 0, At, B0); PG8_MMA(0, 1, At, B1); PG8_BAR; PG8_SCHED;
	s_setprio 3
	v_mfma_f32_16x16x32_bf16 v[42:45], v[152:155], v[184:187], v[42:45]
	v_mfma_f32_16x16x32_bf16 v[42:45], v[156:159], v[216:219], v[42:45]
	v_mfma_f32_16x16x32_bf16 v[46:49], v[148:151], v[216:219], v[46:49]
	v_mfma_f32_16x16x32_bf16 v[46:49], v[144:147], v[184:187], v[46:49]
	v_mfma_f32_16x16x32_bf16 v[30:33], v[144:147], v[220:223], v[30:33]
	v_mfma_f32_16x16x32_bf16 v[30:33], v[148:151], v[224:227], v[30:33]
	v_mfma_f32_16x16x32_bf16 v[22:25], v[156:159], v[224:227], v[22:25]
	v_mfma_f32_16x16x32_bf16 v[22:25], v[152:155], v[220:223], v[22:25]
	v_mfma_f32_16x16x32_bf16 v[6:9], v[152:155], v[230:233], v[6:9]
	v_mfma_f32_16x16x32_bf16 v[6:9], v[156:159], v[234:237], v[6:9]
	v_mfma_f32_16x16x32_bf16 v[14:17], v[148:151], v[234:237], v[14:17]
	v_mfma_f32_16x16x32_bf16 v[14:17], v[144:147], v[230:233], v[14:17]
	s_setprio 0
	s_setprio 3
	v_mfma_f32_16x16x32_bf16 v[54:57], v[160:163], v[176:179], v[54:57]
	v_mfma_f32_16x16x32_bf16 v[54:57], v[164:167], v[180:183], v[54:57]
	v_mfma_f32_16x16x32_bf16 v[50:53], v[172:175], v[180:183], v[50:53]
	v_mfma_f32_16x16x32_bf16 v[50:53], v[168:171], v[176:179], v[50:53]
	v_mfma_f32_16x16x32_bf16 v[34:37], v[168:171], v[184:187], v[34:37]
	v_mfma_f32_16x16x32_bf16 v[34:37], v[172:175], v[216:219], v[34:37]
	v_mfma_f32_16x16x32_bf16 v[38:41], v[164:167], v[216:219], v[38:41]
	v_mfma_f32_16x16x32_bf16 v[38:41], v[160:163], v[184:187], v[38:41]
	v_mfma_f32_16x16x32_bf16 v[26:29], v[160:163], v[220:223], v[26:29]
	v_mfma_f32_16x16x32_bf16 v[26:29], v[164:167], v[224:227], v[26:29]
	v_mfma_f32_16x16x32_bf16 v[18:21], v[172:175], v[224:227], v[18:21]
	v_mfma_f32_16x16x32_bf16 v[18:21], v[168:171], v[220:223], v[18:21]
	v_mfma_f32_16x16x32_bf16 v[2:5], v[168:171], v[230:233], v[2:5]
	v_mfma_f32_16x16x32_bf16 v[2:5], v[172:175], v[234:237], v[2:5]
	v_mfma_f32_16x16x32_bf16 v[10:13], v[164:167], v[234:237], v[10:13]
	v_mfma_f32_16x16x32_bf16 v[10:13], v[160:163], v[230:233], v[10:13]
	s_setprio 0
	s_barrier
	s_add_i32 s60, 0, 0x18000
	v_add_u32_e32 v0, s60, v208
	v_add_u32_e32 v131, s60, v209
	ds_read_b128 v[144:147], v0
	ds_read_b128 v[148:151], v131
	v_add_u32_e32 v0, s66, v208
	s_add_i32 s61, 0, 0x1c000
	v_add_u32_e32 v131, s66, v209
	ds_read_b128 v[152:155], v0
	ds_read_b128 v[156:159], v131
	v_add_u32_e32 v0, s61, v208
	v_add_u32_e32 v131, s61, v209
	ds_read_b128 v[160:163], v0
	ds_read_b128 v[164:167], v131
	v_add_u32_e32 v0, s67, v208
	v_add_u32_e32 v131, s67, v209
	ds_read_b128 v[168:171], v0
	ds_read_b128 v[172:175], v131
	s_add_u32 s48, s58, s92
	s_addc_u32 s49, s59, s91
	s_mov_b32 m0, s34
	ds_read_b128 v[176:179], v212 offset:32768
	ds_read_b128 v[180:183], v212 offset:34816
	ds_read_b128 v[184:187], v213 offset:32768
	ds_read_b128 v[216:219], v213 offset:34816
	ds_read_b128 v[220:223], v212 offset:36864
	ds_read_b128 v[224:227], v212 offset:38912
	ds_read_b128 v[230:233], v213 offset:36864
	ds_read_b128 v[234:237], v213 offset:38912
	global_load_lds_dwordx4 v138, s[48:49]
	s_mov_b32 m0, s35
	s_nop 0
	global_load_lds_dwordx4 v140, s[48:49]
	s_waitcnt vmcnt(8)
	s_waitcnt lgkmcnt(0)
	s_waitcnt lgkmcnt(0)
	v_mfma_f32_16x16x32_bf16 v[126:129], v[144:147], v[176:179], v[126:129]
	v_mfma_f32_16x16x32_bf16 v[126:129], v[148:151], v[184:187], v[126:129]
	v_mfma_f32_16x16x32_bf16 v[122:125], v[156:159], v[184:187], v[122:125]
	v_mfma_f32_16x16x32_bf16 v[122:125], v[152:155], v[176:179], v[122:125]
	s_barrier
	s_setprio 3
	v_mfma_f32_16x16x32_bf16 v[106:109], v[152:155], v[180:183], v[106:109]
	v_mfma_f32_16x16x32_bf16 v[106:109], v[156:159], v[216:219], v[106:109]
	v_mfma_f32_16x16x32_bf16 v[110:113], v[148:151], v[216:219], v[110:113]
	v_mfma_f32_16x16x32_bf16 v[110:113], v[144:147], v[180:183], v[110:113]
	v_mfma_f32_16x16x32_bf16 v[94:97], v[144:147], v[220:223], v[94:97]
	v_mfma_f32_16x16x32_bf16 v[94:97], v[148:151], v[230:233], v[94:97]
	v_mfma_f32_16x16x32_bf16 v[90:93], v[156:159], v[230:233], v[90:93]
	v_mfma_f32_16x16x32_bf16 v[90:93], v[152:155], v[220:223], v[90:93]
	v_mfma_f32_16x16x32_bf16 v[74:77], v[152:155], v[224:227], v[74:77]
	v_mfma_f32_16x16x32_bf16 v[74:77], v[156:159], v[234:237], v[74:77]
	v_mfma_f32_16x16x32_bf16 v[78:81], v[148:151], v[234:237], v[78:81]
	v_mfma_f32_16x16x32_bf16 v[78:81], v[144:147], v[224:227], v[78:81]
	s_setprio 0
	s_setprio 3
	v_mfma_f32_16x16x32_bf16 v[118:121], v[160:163], v[176:179], v[118:121]
	v_mfma_f32_16x16x32_bf16 v[118:121], v[164:167], v[184:187], v[118:121]
	v_mfma_f32_16x16x32_bf16 v[114:117], v[172:175], v[184:187], v[114:117]
	v_mfma_f32_16x16x32_bf16 v[114:117], v[168:171], v[176:179], v[114:117]
	v_mfma_f32_16x16x32_bf16 v[98:101], v[168:171], v[180:183], v[98:101]
	v_mfma_f32_16x16x32_bf16 v[98:101], v[172:175], v[216:219], v[98:101]
	v_mfma_f32_16x16x32_bf16 v[102:105], v[164:167], v[216:219], v[102:105]
	v_mfma_f32_16x16x32_bf16 v[102:105], v[160:163], v[180:183], v[102:105]
	v_mfma_f32_16x16x32_bf16 v[86:89], v[160:163], v[220:223], v[86:89]
	v_mfma_f32_16x16x32_bf16 v[86:89], v[164:167], v[230:233], v[86:89]
	v_mfma_f32_16x16x32_bf16 v[82:85], v[172:175], v[230:233], v[82:85]
	v_mfma_f32_16x16x32_bf16 v[82:85], v[168:171], v[220:223], v[82:85]
	v_mfma_f32_16x16x32_bf16 v[66:69], v[168:171], v[224:227], v[66:69]
	v_mfma_f32_16x16x32_bf16 v[66:69], v[172:175], v[234:237], v[66:69]
	v_mfma_f32_16x16x32_bf16 v[70:73], v[164:167], v[234:237], v[70:73]
	v_mfma_f32_16x16x32_bf16 v[70:73], v[160:163], v[224:227], v[70:73]
	s_setprio 0
	s_barrier
; #define PG8_STAGE(bufoff, gbase, voff) do { _Pragma("unroll") for (int _i = 0; _i < 2; ++_i) \
;         __builtin_amdgcn_global_load_lds((const unsigned*)((const char*)(gbase) + (voff)[_i]), (LAS unsigned*)(lds + (bufoff) + ldsw + _i * 8192), 16, 0, 0); } while (0)
; #define PG8_LDA(dst, b, h) do { _Pragma("unroll") for (int m = 0; m < 4; ++m) _Pragma("unroll") for (int k = 0; k < 2; ++k) dst[m][k] = *(const LAS bf16x8*)(lds + PG8_SA(b, h) + aoffk[k] + m * 2048); } while (0)
; #define PG8_WAIT_V(n) asm volatile("s_waitcnt vmcnt(" #n ")" ::: "memory")
; #define PG8_WAIT_L(n) asm volatile("s_waitcnt lgkmcnt(" #n ")" ::: "memory")
; #define PG8_BAR __builtin_amdgcn_s_barrier()
; #define PG8_SCHED __builtin_amdgcn_sched_barrier(0)
;     __device__ __forceinline__ void mid(Acc& acc, const Unit& u, int s, int wr, int wc, int fr, int fq) const {
;         int lo = (wr * 4 + wc) * 8192 + (fq * 16 + fr) * 16; asm volatile("" : "+v"(lo));
;         const unsigned char* gp = gate + ((size_t)(u.pm * 48 + s * 16 + u.pn) << 16) + lo;
;         u32x4 G[8][2];
; #pragma unroll
;         for (int i = 0; i < 8; ++i) { G[i][0] = __builtin_nontemporal_load((const u32x4*)(gp + i * 1024)); G[i][1] = __builtin_nontemporal_load((const u32x4*)(gp + (1 << 20) + i * 1024)); }
; template <class Epi, class Sched, class GemmT>
; __device__ __forceinline__ void gemm_phase(LAS unsigned char* lds, const GemmT& g, const Sched& S, const Epi& E, const int wid) {
;     ...
;                 PG8_WAIT_V(8); PG8_WAIT_L(0); PG8_BAR; PG8_MMA(0, 0, At, B0); PG8_MMA(0, 1, At, B1); PG8_BAR; PG8_SCHED;
;                 PG8_LDA(At, 1, 1); PG8_STAGE(PG8_SB(1, 0), b3, vB2); PG8_STAGE(PG8_SB(1, 1), b3 + hB2, vB2); PG8_STAGE(PG8_SA(1, 0), a3, vA2);
;                 PG8_WAIT_V(8); PG8_WAIT_L(0); PG8_BAR; PG8_MMA(1, 0, At, B0); PG8_MMA(1, 1, At, B1); PG8_BAR; PG8_SCHED;
;             }
;             if constexpr (NSEG > 1) { if (sgi + 1 < NSEG) E.mid(acc, cur, sgi, wr, wc, fr, fq); }
;             cs = ns; cA = ns.A; cB = ns.B; hstepA = nhA; hstepB = nhB;
; #pragma unroll
;             for (int i = 0; i < 2; ++i) { voffA[i] = nvA[i]; voffB[i] = nvB[i]; }
	s_add_i32 s48, s60, s68
	v_lshl_add_u64 v[202:203], v[202:203], 0, s[20:21]
	s_mov_b32 m0, s48
	ds_read_b128 v[138:141], v212 offset:49152
	ds_read_b128 v[176:179], v212 offset:51200
	ds_read_b128 v[180:183], v213 offset:49152
	ds_read_b128 v[184:187], v213 offset:51200
	ds_read_b128 v[216:219], v212 offset:53248
	ds_read_b128 v[220:223], v212 offset:55296
	ds_read_b128 v[224:227], v213 offset:53248
	ds_read_b128 v[230:233], v213 offset:55296
	global_load_lds_dwordx4 v[202:203], off
	v_lshl_add_u64 v[202:203], v[238:239], 0, s[20:21]
	s_add_i32 m0, s48, 0x2000
	s_add_i32 s48, s61, s68
	global_load_lds_dwordx4 v[202:203], off
	v_lshl_add_u64 v[202:203], v[240:241], 0, s[20:21]
	s_mov_b32 m0, s48
	v_lshl_add_u64 v[188:189], v[188:189], 0, s[20:21]
	global_load_lds_dwordx4 v[202:203], off
	v_lshl_add_u64 v[202:203], v[242:243], 0, s[20:21]
	s_add_i32 m0, s48, 0x2000
	s_nop 0
	global_load_lds_dwordx4 v[202:203], off
	s_mov_b32 m0, s54
	s_nop 0
	global_load_lds_dwordx4 v[188:189], off
	v_lshl_add_u64 v[188:189], v[244:245], 0, s[20:21]
	s_mov_b32 m0, s55
	s_nop 0
	global_load_lds_dwordx4 v[188:189], off
	s_waitcnt vmcnt(8)
	s_waitcnt lgkmcnt(0)
	s_waitcnt lgkmcnt(0)
	v_mfma_f32_16x16x32_bf16 v[62:65], v[144:147], v[138:141], v[62:65]
	v_mfma_f32_16x16x32_bf16 v[62:65], v[148:151], v[180:183], v[62:65]
	v_mfma_f32_16x16x32_bf16 v[58:61], v[156:159], v[180:183], v[58:61]
	v_mfma_f32_16x16x32_bf16 v[58:61], v[152:155], v[138:141], v[58:61]
	s_barrier
	s_setprio 3
	v_mfma_f32_16x16x32_bf16 v[42:45], v[152:155], v[176:179], v[42:45]
	v_mfma_f32_16x16x32_bf16 v[42:45], v[156:159], v[184:187], v[42:45]
	v_mfma_f32_16x16x32_bf16 v[46:49], v[148:151], v[184:187], v[46:49]
	v_mfma_f32_16x16x32_bf16 v[46:49], v[144:147], v[176:179], v[46:49]
	v_mfma_f32_16x16x32_bf16 v[30:33], v[144:147], v[216:219], v[30:33]
	v_mfma_f32_16x16x32_bf16 v[30:33], v[148:151], v[224:227], v[30:33]
	v_mfma_f32_16x16x32_bf16 v[22:25], v[156:159], v[224:227], v[22:25]
	v_mfma_f32_16x16x32_bf16 v[22:25], v[152:155], v[216:219], v[22:25]
	v_mfma_f32_16x16x32_bf16 v[6:9], v[152:155], v[220:223], v[6:9]
	v_mfma_f32_16x16x32_bf16 v[6:9], v[156:159], v[230:233], v[6:9]
	v_mfma_f32_16x16x32_bf16 v[14:17], v[148:151], v[230:233], v[14:17]
	v_mfma_f32_16x16x32_bf16 v[14:17], v[144:147], v[220:223], v[14:17]
	s_setprio 0
	s_setprio 3
	v_mfma_f32_16x16x32_bf16 v[54:57], v[160:163], v[138:141], v[54:57]
	v_mfma_f32_16x16x32_bf16 v[54:57], v[164:167], v[180:183], v[54:57]
	v_mfma_f32_16x16x32_bf16 v[50:53], v[172:175], v[180:183], v[50:53]
	v_mfma_f32_16x16x32_bf16 v[50:53], v[168:171], v[138:141], v[50:53]
	v_mfma_f32_16x16x32_bf16 v[34:37], v[168:171], v[176:179], v[34:37]
	v_mfma_f32_16x16x32_bf16 v[34:37], v[172:175], v[184:187], v[34:37]
	v_mfma_f32_16x16x32_bf16 v[38:41], v[164:167], v[184:187], v[38:41]
	v_mfma_f32_16x16x32_bf16 v[38:41], v[160:163], v[176:179], v[38:41]
	v_mfma_f32_16x16x32_bf16 v[26:29], v[160:163], v[216:219], v[26:29]
	v_mfma_f32_16x16x32_bf16 v[26:29], v[164:167], v[224:227], v[26:29]
	v_mfma_f32_16x16x32_bf16 v[18:21], v[172:175], v[224:227], v[18:21]
	v_mfma_f32_16x16x32_bf16 v[18:21], v[168:171], v[216:219], v[18:21]
	v_mfma_f32_16x16x32_bf16 v[2:5], v[168:171], v[220:223], v[2:5]
	v_mfma_f32_16x16x32_bf16 v[2:5], v[172:175], v[230:233], v[2:5]
	v_mfma_f32_16x16x32_bf16 v[10:13], v[164:167], v[230:233], v[10:13]
	v_mfma_f32_16x16x32_bf16 v[10:13], v[160:163], v[220:223], v[10:13]
	s_setprio 0
	s_add_u32 s56, s56, 0x100
	s_addc_u32 s57, s57, 0
	s_cmp_ge_u32 s90, s42
	s_barrier
	s_cbranch_scc0 .LBB0_764
	s_and_b64 vcc, exec, s[52:53]
	s_cbranch_vccz .LBB0_767
	s_lshl_b32 s42, s83, 4
	s_add_i32 s42, s82, s42
	s_ashr_i32 s43, s42, 31
	s_lshl_b64 s[42:43], s[42:43], 16
	v_mov_b32_e32 v130, v210
	s_add_u32 s42, s22, s42
	s_addc_u32 s43, s23, s43
	v_ashrrev_i32_e32 v131, 31, v130
	v_lshl_add_u64 v[130:131], s[42:43], 0, v[130:131]
	v_add_co_u32_e32 v132, vcc, s69, v130
	s_mov_b32 s42, 0x101000
	s_nop 0
	v_addc_co_u32_e32 v133, vcc, 0, v131, vcc
	global_load_dwordx4 v[186:189], v[130:131], off nt
	v_add_co_u32_e32 v134, vcc, s42, v130
	s_movk_i32 s42, 0x1000
	s_nop 0
	v_addc_co_u32_e32 v135, vcc, 0, v131, vcc
	global_load_dwordx4 v[216:219], v[134:135], off offset:-4096 nt
	global_load_dwordx4 v[178:181], v[130:131], off offset:1024 nt
	global_load_dwordx4 v[182:185], v[132:133], off offset:1024 nt
	global_load_dwordx4 v[170:173], v[130:131], off offset:2048 nt
	global_load_dwordx4 v[174:177], v[132:133], off offset:2048 nt
	global_load_dwordx4 v[162:165], v[130:131], off offset:3072 nt
	global_load_dwordx4 v[166:169], v[132:133], off offset:3072 nt
	v_add_co_u32_e32 v130, vcc, s42, v130
	s_waitcnt vmcnt(0)
;     __device__ __forceinline__ void mid(Acc& acc, const Unit& u, int s, int wr, int wc, int fr, int fq) const {
;     ...
;         for (int i = 0; i < 8; ++i) { G[i][0] = __builtin_nontemporal_load((const u32x4*)(gp + i * 1024)); G[i][1] = __builtin_nontemporal_load((const u32x4*)(gp + (1 << 20) + i * 1024)); }
; #pragma unroll
;         for (int i = 0; i < 8; ++i) { const int ai = i >> 2, m = i & 3;
; #pragma unroll
;             for (int bj = 0; bj < 2; ++bj) {
;                 const u32x4 ga = G[i][0], gb = G[i][1];
;                 const u32x2 wa = bj == 0 ? (u32x2){ga.x, ga.y} : (u32x2){ga.z, ga.w}, wb = bj == 0 ? (u32x2){gb.x, gb.y} : (u32x2){gb.z, gb.w};
;                 float fa[8], fb[8]; gate_unpack8(wa, fa); gate_unpack8(wb, fb);
; #pragma unroll
;                 for (int e = 0; e < 8; ++e) fa[e] = fa[e] * __builtin_amdgcn_rcpf(fb[e]);
;                 f32x4& v0 = acc[ai][bj][m][0]; f32x4& v1 = acc[ai][bj][m][1];
;                 v0[0] *= fa[0]; v0[1] *= fa[1]; v0[2] *= fa[2]; v0[3] *= fa[3]; v1[0] *= fa[4]; v1[1] *= fa[5]; v1[2] *= fa[6]; v1[3] *= fa[7]; }
;             __builtin_amdgcn_sched_barrier(0); }
	v_cvt_f32_ubyte0_e32 v0, v216
	v_addc_co_u32_e32 v131, vcc, 0, v131, vcc
	global_load_dwordx4 v[154:157], v[130:131], off nt
	global_load_dwordx4 v[158:161], v[134:135], off nt
	global_load_dwordx4 v[146:149], v[130:131], off offset:1024 nt
	global_load_dwordx4 v[150:153], v[134:135], off offset:1024 nt
	global_load_dwordx4 v[138:141], v[130:131], off offset:2048 nt
	global_load_dwordx4 v[142:145], v[134:135], off offset:2048 nt
	s_nop 0
	global_load_dwordx4 v[130:133], v[130:131], off offset:3072 nt
	s_nop 0
	global_load_dwordx4 v[134:137], v[134:135], off offset:3072 nt
	v_cvt_f32_ubyte1_e32 v203, v216
	v_cvt_f32_ubyte2_e32 v215, v216
	v_cvt_f32_ubyte3_e32 v220, v216
	v_cvt_f32_ubyte0_e32 v221, v217
	v_cvt_f32_ubyte1_e32 v222, v217
	v_cvt_f32_ubyte2_e32 v223, v217
	v_cvt_f32_ubyte3_e32 v224, v217
	v_rcp_iflag_f32_e32 v202, v0
	v_rcp_iflag_f32_e32 v203, v203
	v_rcp_iflag_f32_e32 v216, v215
	v_rcp_iflag_f32_e32 v217, v220
	v_rcp_iflag_f32_e32 v220, v221
	v_rcp_iflag_f32_e32 v221, v222
	v_rcp_iflag_f32_e32 v222, v223
	v_rcp_iflag_f32_e32 v223, v224
	v_cvt_f32_ubyte3_e32 v225, v186
	v_cvt_f32_ubyte2_e32 v224, v186
	v_cvt_f32_ubyte1_e32 v227, v186
	v_cvt_f32_ubyte0_e32 v226, v186
	v_pk_mul_f32 v[202:203], v[202:203], v[226:227]
	v_pk_mul_f32 v[216:217], v[216:217], v[224:225]
	v_pk_mul_f32 v[126:127], v[126:127], v[202:203]
	v_pk_mul_f32 v[128:129], v[128:129], v[216:217]
	v_cvt_f32_ubyte3_e32 v203, v187
	v_cvt_f32_ubyte2_e32 v202, v187
	v_cvt_f32_ubyte1_e32 v217, v187
	v_cvt_f32_ubyte0_e32 v216, v187
	v_pk_mul_f32 v[186:187], v[220:221], v[216:217]
	v_pk_mul_f32 v[202:203], v[222:223], v[202:203]
	v_pk_mul_f32 v[122:123], v[122:123], v[186:187]
	v_pk_mul_f32 v[124:125], v[124:125], v[202:203]
	v_cvt_f32_ubyte0_e32 v0, v218
	v_cvt_f32_ubyte1_e32 v186, v218
	v_cvt_f32_ubyte2_e32 v187, v218
	v_cvt_f32_ubyte3_e32 v202, v218
	v_cvt_f32_ubyte0_e32 v203, v219
	v_cvt_f32_ubyte1_e32 v215, v219
	v_cvt_f32_ubyte2_e32 v220, v219
	v_cvt_f32_ubyte3_e32 v221, v219
	v_rcp_iflag_f32_e32 v216, v0
	v_rcp_iflag_f32_e32 v217, v186
	v_rcp_iflag_f32_e32 v218, v187
	v_rcp_iflag_f32_e32 v219, v202
	v_rcp_iflag_f32_e32 v202, v203
	v_rcp_iflag_f32_e32 v203, v215
	v_rcp_iflag_f32_e32 v186, v220
	v_rcp_iflag_f32_e32 v187, v221
	v_cvt_f32_ubyte3_e32 v221, v188
	v_cvt_f32_ubyte2_e32 v220, v188
	v_cvt_f32_ubyte1_e32 v223, v188
	v_cvt_f32_ubyte0_e32 v222, v188
	v_pk_mul_f32 v[216:217], v[216:217], v[222:223]
	v_pk_mul_f32 v[218:219], v[218:219], v[220:221]
	v_pk_mul_f32 v[118:119], v[118:119], v[216:217]
	v_pk_mul_f32 v[120:121], v[120:121], v[218:219]
	v_cvt_f32_ubyte3_e32 v217, v189
	v_cvt_f32_ubyte2_e32 v216, v189
	v_cvt_f32_ubyte1_e32 v219, v189
	v_cvt_f32_ubyte0_e32 v218, v189
	v_pk_mul_f32 v[188:189], v[202:203], v[218:219]
	v_pk_mul_f32 v[186:187], v[186:187], v[216:217]
	v_pk_mul_f32 v[114:115], v[114:115], v[188:189]
	v_pk_mul_f32 v[116:117], v[116:117], v[186:187]
	v_cvt_f32_ubyte0_e32 v0, v182
	v_cvt_f32_ubyte1_e32 v186, v182
	v_cvt_f32_ubyte2_e32 v187, v182
	v_cvt_f32_ubyte3_e32 v188, v182
	v_cvt_f32_ubyte0_e32 v189, v183
	v_cvt_f32_ubyte1_e32 v202, v183
	v_cvt_f32_ubyte2_e32 v203, v183
	v_cvt_f32_ubyte3_e32 v215, v183
	v_rcp_iflag_f32_e32 v182, v0
	v_rcp_iflag_f32_e32 v183, v186
	v_rcp_iflag_f32_e32 v186, v187
	v_rcp_iflag_f32_e32 v187, v188
	v_rcp_iflag_f32_e32 v188, v189
	v_rcp_iflag_f32_e32 v189, v202
	v_rcp_iflag_f32_e32 v202, v203
	v_rcp_iflag_f32_e32 v203, v215
	v_cvt_f32_ubyte3_e32 v217, v178
	v_cvt_f32_ubyte2_e32 v216, v178
	v_cvt_f32_ubyte1_e32 v219, v178
	v_cvt_f32_ubyte0_e32 v218, v178
	v_pk_mul_f32 v[182:183], v[182:183], v[218:219]
	v_pk_mul_f32 v[186:187], v[186:187], v[216:217]
	v_pk_mul_f32 v[110:111], v[110:111], v[182:183]
	v_pk_mul_f32 v[112:113], v[112:113], v[186:187]
	v_cvt_f32_ubyte3_e32 v183, v179
	v_cvt_f32_ubyte2_e32 v182, v179
	v_cvt_f32_ubyte1_e32 v187, v179
	v_cvt_f32_ubyte0_e32 v186, v179
	v_pk_mul_f32 v[178:179], v[188:189], v[186:187]
	v_pk_mul_f32 v[182:183], v[202:203], v[182:183]
	v_pk_mul_f32 v[106:107], v[106:107], v[178:179]
	v_pk_mul_f32 v[108:109], v[108:109], v[182:183]
	v_cvt_f32_ubyte0_e32 v0, v184
	v_cvt_f32_ubyte1_e32 v179, v184
	v_cvt_f32_ubyte2_e32 v182, v184
	v_cvt_f32_ubyte3_e32 v183, v184
	v_rcp_iflag_f32_e32 v178, v0
	v_rcp_iflag_f32_e32 v179, v179
	v_rcp_iflag_f32_e32 v182, v182
	v_rcp_iflag_f32_e32 v183, v183
	v_cvt_f32_ubyte0_e32 v184, v185
	v_cvt_f32_ubyte1_e32 v186, v185
	v_cvt_f32_ubyte2_e32 v187, v185
	v_cvt_f32_ubyte3_e32 v188, v185
	v_rcp_iflag_f32_e32 v184, v184
	v_rcp_iflag_f32_e32 v185, v186
	v_rcp_iflag_f32_e32 v186, v187
	v_rcp_iflag_f32_e32 v187, v188
	v_cvt_f32_ubyte3_e32 v189, v180
	v_cvt_f32_ubyte2_e32 v188, v180
	v_cvt_f32_ubyte1_e32 v203, v180
	v_cvt_f32_ubyte0_e32 v202, v180
	v_pk_mul_f32 v[178:179], v[178:179], v[202:203]
	v_pk_mul_f32 v[182:183], v[182:183], v[188:189]
	v_pk_mul_f32 v[102:103], v[102:103], v[178:179]
	v_pk_mul_f32 v[104:105], v[104:105], v[182:183]
	v_cvt_f32_ubyte3_e32 v179, v181
	v_cvt_f32_ubyte2_e32 v178, v181
	v_cvt_f32_ubyte1_e32 v183, v181
	v_cvt_f32_ubyte0_e32 v182, v181
	v_pk_mul_f32 v[180:181], v[184:185], v[182:183]
	v_pk_mul_f32 v[178:179], v[186:187], v[178:179]
	v_pk_mul_f32 v[98:99], v[98:99], v[180:181]
	v_pk_mul_f32 v[100:101], v[100:101], v[178:179]
	v_cvt_f32_ubyte0_e32 v0, v174
	v_cvt_f32_ubyte1_e32 v178, v174
	v_cvt_f32_ubyte2_e32 v179, v174
	v_cvt_f32_ubyte3_e32 v180, v174
	v_cvt_f32_ubyte0_e32 v181, v175
	v_cvt_f32_ubyte1_e32 v182, v175
	v_cvt_f32_ubyte2_e32 v183, v175
	v_cvt_f32_ubyte3_e32 v184, v175
	v_rcp_iflag_f32_e32 v174, v0
	v_rcp_iflag_f32_e32 v175, v178
	v_rcp_iflag_f32_e32 v178, v179
	v_rcp_iflag_f32_e32 v179, v180
	v_rcp_iflag_f32_e32 v180, v181
;     __device__ __forceinline__ void mid(Acc& acc, const Unit& u, int s, int wr, int wc, int fr, int fq) const {
;     ...
;         for (int i = 0; i < 8; ++i) { const int ai = i >> 2, m = i & 3;
; #pragma unroll
;             for (int bj = 0; bj < 2; ++bj) {
;                 const u32x4 ga = G[i][0], gb = G[i][1];
;                 const u32x2 wa = bj == 0 ? (u32x2){ga.x, ga.y} : (u32x2){ga.z, ga.w}, wb = bj == 0 ? (u32x2){gb.x, gb.y} : (u32x2){gb.z, gb.w};
;                 float fa[8], fb[8]; gate_unpack8(wa, fa); gate_unpack8(wb, fb);
; #pragma unroll
;                 for (int e = 0; e < 8; ++e) fa[e] = fa[e] * __builtin_amdgcn_rcpf(fb[e]);
;                 f32x4& v0 = acc[ai][bj][m][0]; f32x4& v1 = acc[ai][bj][m][1];
;                 v0[0] *= fa[0]; v0[1] *= fa[1]; v0[2] *= fa[2]; v0[3] *= fa[3]; v1[0] *= fa[4]; v1[1] *= fa[5]; v1[2] *= fa[6]; v1[3] *= fa[7]; }
;             __builtin_amdgcn_sched_barrier(0); }
	v_rcp_iflag_f32_e32 v181, v182
	v_rcp_iflag_f32_e32 v182, v183
	v_rcp_iflag_f32_e32 v183, v184
	v_cvt_f32_ubyte3_e32 v185, v170
	v_cvt_f32_ubyte2_e32 v184, v170
	v_cvt_f32_ubyte1_e32 v187, v170
	v_cvt_f32_ubyte0_e32 v186, v170
	v_pk_mul_f32 v[174:175], v[174:175], v[186:187]
	v_pk_mul_f32 v[178:179], v[178:179], v[184:185]
	v_pk_mul_f32 v[94:95], v[94:95], v[174:175]
	v_pk_mul_f32 v[96:97], v[96:97], v[178:179]
	v_cvt_f32_ubyte3_e32 v175, v171
	v_cvt_f32_ubyte2_e32 v174, v171
	v_cvt_f32_ubyte1_e32 v179, v171
	v_cvt_f32_ubyte0_e32 v178, v171
	v_pk_mul_f32 v[170:171], v[180:181], v[178:179]
	v_pk_mul_f32 v[174:175], v[182:183], v[174:175]
	v_pk_mul_f32 v[90:91], v[90:91], v[170:171]
	v_pk_mul_f32 v[92:93], v[92:93], v[174:175]
	v_cvt_f32_ubyte0_e32 v0, v176
	v_cvt_f32_ubyte1_e32 v171, v176
	v_cvt_f32_ubyte2_e32 v174, v176
	v_cvt_f32_ubyte3_e32 v175, v176
	v_rcp_iflag_f32_e32 v170, v0
	v_rcp_iflag_f32_e32 v171, v171
	v_rcp_iflag_f32_e32 v174, v174
	v_rcp_iflag_f32_e32 v175, v175
	v_cvt_f32_ubyte0_e32 v176, v177
	v_cvt_f32_ubyte1_e32 v178, v177
	v_cvt_f32_ubyte2_e32 v179, v177
	v_cvt_f32_ubyte3_e32 v180, v177
	v_rcp_iflag_f32_e32 v176, v176
	v_rcp_iflag_f32_e32 v177, v178
	v_rcp_iflag_f32_e32 v178, v179
	v_rcp_iflag_f32_e32 v179, v180
	v_cvt_f32_ubyte3_e32 v181, v172
	v_cvt_f32_ubyte2_e32 v180, v172
	v_cvt_f32_ubyte1_e32 v183, v172
	v_cvt_f32_ubyte0_e32 v182, v172
	v_pk_mul_f32 v[170:171], v[170:171], v[182:183]
	v_pk_mul_f32 v[174:175], v[174:175], v[180:181]
	v_pk_mul_f32 v[86:87], v[86:87], v[170:171]
	v_pk_mul_f32 v[88:89], v[88:89], v[174:175]
	v_cvt_f32_ubyte3_e32 v171, v173
	v_cvt_f32_ubyte2_e32 v170, v173
	v_cvt_f32_ubyte1_e32 v175, v173
	v_cvt_f32_ubyte0_e32 v174, v173
	v_pk_mul_f32 v[172:173], v[176:177], v[174:175]
	v_pk_mul_f32 v[170:171], v[178:179], v[170:171]
	v_pk_mul_f32 v[82:83], v[82:83], v[172:173]
	v_pk_mul_f32 v[84:85], v[84:85], v[170:171]
	v_cvt_f32_ubyte0_e32 v0, v166
	v_cvt_f32_ubyte1_e32 v170, v166
	v_cvt_f32_ubyte2_e32 v171, v166
	v_cvt_f32_ubyte3_e32 v172, v166
	v_cvt_f32_ubyte0_e32 v173, v167
	v_cvt_f32_ubyte1_e32 v174, v167
	v_cvt_f32_ubyte2_e32 v175, v167
	v_cvt_f32_ubyte3_e32 v176, v167
	v_rcp_iflag_f32_e32 v166, v0
	v_rcp_iflag_f32_e32 v167, v170
	v_rcp_iflag_f32_e32 v170, v171
	v_rcp_iflag_f32_e32 v171, v172
	v_rcp_iflag_f32_e32 v172, v173
	v_rcp_iflag_f32_e32 v173, v174
	v_rcp_iflag_f32_e32 v174, v175
	v_rcp_iflag_f32_e32 v175, v176
	v_cvt_f32_ubyte3_e32 v177, v162
	v_cvt_f32_ubyte2_e32 v176, v162
	v_cvt_f32_ubyte1_e32 v179, v162
	v_cvt_f32_ubyte0_e32 v178, v162
	v_pk_mul_f32 v[166:167], v[166:167], v[178:179]
	v_pk_mul_f32 v[170:171], v[170:171], v[176:177]
	v_pk_mul_f32 v[78:79], v[78:79], v[166:167]
	v_pk_mul_f32 v[80:81], v[80:81], v[170:171]
	v_cvt_f32_ubyte3_e32 v167, v163
	v_cvt_f32_ubyte2_e32 v166, v163
	v_cvt_f32_ubyte1_e32 v171, v163
	v_cvt_f32_ubyte0_e32 v170, v163
	v_pk_mul_f32 v[162:163], v[172:173], v[170:171]
	v_pk_mul_f32 v[166:167], v[174:175], v[166:167]
	v_pk_mul_f32 v[74:75], v[74:75], v[162:163]
	v_pk_mul_f32 v[76:77], v[76:77], v[166:167]
	v_cvt_f32_ubyte0_e32 v0, v168
	v_cvt_f32_ubyte1_e32 v163, v168
	v_cvt_f32_ubyte2_e32 v166, v168
	v_cvt_f32_ubyte3_e32 v167, v168
	v_rcp_iflag_f32_e32 v162, v0
	v_rcp_iflag_f32_e32 v163, v163
	v_rcp_iflag_f32_e32 v166, v166
	v_rcp_iflag_f32_e32 v167, v167
	v_cvt_f32_ubyte0_e32 v168, v169
	v_cvt_f32_ubyte1_e32 v170, v169
	v_cvt_f32_ubyte2_e32 v171, v169
	v_cvt_f32_ubyte3_e32 v172, v169
	v_rcp_iflag_f32_e32 v168, v168
	v_rcp_iflag_f32_e32 v169, v170
	v_rcp_iflag_f32_e32 v170, v171
	v_rcp_iflag_f32_e32 v171, v172
	v_cvt_f32_ubyte3_e32 v173, v164
	v_cvt_f32_ubyte2_e32 v172, v164
	v_cvt_f32_ubyte1_e32 v175, v164
	v_cvt_f32_ubyte0_e32 v174, v164
	v_pk_mul_f32 v[162:163], v[162:163], v[174:175]
	v_pk_mul_f32 v[166:167], v[166:167], v[172:173]
	v_pk_mul_f32 v[70:71], v[70:71], v[162:163]
	v_pk_mul_f32 v[72:73], v[72:73], v[166:167]
	v_cvt_f32_ubyte3_e32 v163, v165
	v_cvt_f32_ubyte2_e32 v162, v165
	v_cvt_f32_ubyte1_e32 v167, v165
	v_cvt_f32_ubyte0_e32 v166, v165
	v_pk_mul_f32 v[164:165], v[168:169], v[166:167]
	v_pk_mul_f32 v[162:163], v[170:171], v[162:163]
	v_pk_mul_f32 v[66:67], v[66:67], v[164:165]
	v_pk_mul_f32 v[68:69], v[68:69], v[162:163]
	s_waitcnt vmcnt(6)
	v_cvt_f32_ubyte0_e32 v0, v158
	v_cvt_f32_ubyte1_e32 v162, v158
	v_cvt_f32_ubyte2_e32 v163, v158
	v_cvt_f32_ubyte3_e32 v164, v158
	v_cvt_f32_ubyte0_e32 v165, v159
	v_cvt_f32_ubyte1_e32 v166, v159
	v_cvt_f32_ubyte2_e32 v167, v159
	v_cvt_f32_ubyte3_e32 v168, v159
	v_rcp_iflag_f32_e32 v158, v0
	v_rcp_iflag_f32_e32 v159, v162
	v_rcp_iflag_f32_e32 v162, v163
	v_rcp_iflag_f32_e32 v163, v164
	v_rcp_iflag_f32_e32 v164, v165
	v_rcp_iflag_f32_e32 v165, v166
	v_rcp_iflag_f32_e32 v166, v167
	v_rcp_iflag_f32_e32 v167, v168
	v_cvt_f32_ubyte3_e32 v169, v154
	v_cvt_f32_ubyte2_e32 v168, v154
	v_cvt_f32_ubyte1_e32 v171, v154
	v_cvt_f32_ubyte0_e32 v170, v154
	v_pk_mul_f32 v[158:159], v[158:159], v[170:171]
	v_pk_mul_f32 v[162:163], v[162:163], v[168:169]
	v_pk_mul_f32 v[62:63], v[62:63], v[158:159]
	v_pk_mul_f32 v[64:65], v[64:65], v[162:163]
	v_cvt_f32_ubyte3_e32 v159, v155
	v_cvt_f32_ubyte2_e32 v158, v155
	v_cvt_f32_ubyte1_e32 v163, v155
	v_cvt_f32_ubyte0_e32 v162, v155
	v_pk_mul_f32 v[154:155], v[164:165], v[162:163]
	v_pk_mul_f32 v[158:159], v[166:167], v[158:159]
	v_pk_mul_f32 v[58:59], v[58:59], v[154:155]
	v_pk_mul_f32 v[60:61], v[60:61], v[158:159]
	v_cvt_f32_ubyte0_e32 v0, v160
	v_cvt_f32_ubyte1_e32 v155, v160
	v_cvt_f32_ubyte2_e32 v158, v160
	v_cvt_f32_ubyte3_e32 v159, v160
	v_rcp_iflag_f32_e32 v154, v0
	v_rcp_iflag_f32_e32 v155, v155
	v_rcp_iflag_f32_e32 v158, v158
	v_rcp_iflag_f32_e32 v159, v159
	v_cvt_f32_ubyte0_e32 v160, v161
	v_cvt_f32_ubyte1_e32 v162, v161
	v_cvt_f32_ubyte2_e32 v163, v161
	v_cvt_f32_ubyte3_e32 v164, v161
	v_rcp_iflag_f32_e32 v160, v160
	v_rcp_iflag_f32_e32 v161, v162
	v_rcp_iflag_f32_e32 v162, v163
	v_rcp_iflag_f32_e32 v163, v164
	v_cvt_f32_ubyte3_e32 v165, v156
	v_cvt_f32_ubyte2_e32 v164, v156
	v_cvt_f32_ubyte1_e32 v167, v156
	v_cvt_f32_ubyte0_e32 v166, v156
	v_pk_mul_f32 v[154:155], v[154:155], v[166:167]
	v_pk_mul_f32 v[158:159], v[158:159], v[164:165]
	v_pk_mul_f32 v[54:55], v[54:55], v[154:155]
	v_pk_mul_f32 v[56:57], v[56:57], v[158:159]
	v_cvt_f32_ubyte3_e32 v155, v157
	v_cvt_f32_ubyte2_e32 v154, v157
	v_cvt_f32_ubyte1_e32 v159, v157
	v_cvt_f32_ubyte0_e32 v158, v157
	v_pk_mul_f32 v[156:157], v[160:161], v[158:159]
	v_pk_mul_f32 v[154:155], v[162:163], v[154:155]
	v_pk_mul_f32 v[50:51], v[50:51], v[156:157]
	v_pk_mul_f32 v[52:53], v[52:53], v[154:155]
	s_waitcnt vmcnt(4)
;     __device__ __forceinline__ void mid(Acc& acc, const Unit& u, int s, int wr, int wc, int fr, int fq) const {
;     ...
;         for (int i = 0; i < 8; ++i) { const int ai = i >> 2, m = i & 3;
; #pragma unroll
;             for (int bj = 0; bj < 2; ++bj) {
;                 const u32x4 ga = G[i][0], gb = G[i][1];
;                 const u32x2 wa = bj == 0 ? (u32x2){ga.x, ga.y} : (u32x2){ga.z, ga.w}, wb = bj == 0 ? (u32x2){gb.x, gb.y} : (u32x2){gb.z, gb.w};
;                 float fa[8], fb[8]; gate_unpack8(wa, fa); gate_unpack8(wb, fb);
; #pragma unroll
;                 for (int e = 0; e < 8; ++e) fa[e] = fa[e] * __builtin_amdgcn_rcpf(fb[e]);
;                 f32x4& v0 = acc[ai][bj][m][0]; f32x4& v1 = acc[ai][bj][m][1];
;                 v0[0] *= fa[0]; v0[1] *= fa[1]; v0[2] *= fa[2]; v0[3] *= fa[3]; v1[0] *= fa[4]; v1[1] *= fa[5]; v1[2] *= fa[6]; v1[3] *= fa[7]; }
;             __builtin_amdgcn_sched_barrier(0); }
	v_cvt_f32_ubyte0_e32 v0, v150
	v_cvt_f32_ubyte1_e32 v154, v150
	v_cvt_f32_ubyte2_e32 v155, v150
	v_cvt_f32_ubyte3_e32 v156, v150
	v_cvt_f32_ubyte0_e32 v157, v151
	v_cvt_f32_ubyte1_e32 v158, v151
	v_cvt_f32_ubyte2_e32 v159, v151
	v_cvt_f32_ubyte3_e32 v160, v151
	v_rcp_iflag_f32_e32 v150, v0
	v_rcp_iflag_f32_e32 v151, v154
	v_rcp_iflag_f32_e32 v154, v155
	v_rcp_iflag_f32_e32 v155, v156
	v_rcp_iflag_f32_e32 v156, v157
	v_rcp_iflag_f32_e32 v157, v158
	v_rcp_iflag_f32_e32 v158, v159
	v_rcp_iflag_f32_e32 v159, v160
	v_cvt_f32_ubyte3_e32 v161, v146
	v_cvt_f32_ubyte2_e32 v160, v146
	v_cvt_f32_ubyte1_e32 v163, v146
	v_cvt_f32_ubyte0_e32 v162, v146
	v_pk_mul_f32 v[150:151], v[150:151], v[162:163]
	v_pk_mul_f32 v[154:155], v[154:155], v[160:161]
	v_pk_mul_f32 v[46:47], v[46:47], v[150:151]
	v_pk_mul_f32 v[48:49], v[48:49], v[154:155]
	v_cvt_f32_ubyte3_e32 v151, v147
	v_cvt_f32_ubyte2_e32 v150, v147
	v_cvt_f32_ubyte1_e32 v155, v147
	v_cvt_f32_ubyte0_e32 v154, v147
	v_pk_mul_f32 v[146:147], v[156:157], v[154:155]
	v_pk_mul_f32 v[150:151], v[158:159], v[150:151]
	v_pk_mul_f32 v[42:43], v[42:43], v[146:147]
	v_pk_mul_f32 v[44:45], v[44:45], v[150:151]
	v_cvt_f32_ubyte0_e32 v0, v152
	v_cvt_f32_ubyte1_e32 v147, v152
	v_cvt_f32_ubyte2_e32 v150, v152
	v_cvt_f32_ubyte3_e32 v151, v152
	v_rcp_iflag_f32_e32 v146, v0
	v_rcp_iflag_f32_e32 v147, v147
	v_rcp_iflag_f32_e32 v150, v150
	v_rcp_iflag_f32_e32 v151, v151
	v_cvt_f32_ubyte0_e32 v152, v153
	v_cvt_f32_ubyte1_e32 v154, v153
	v_cvt_f32_ubyte2_e32 v155, v153
	v_cvt_f32_ubyte3_e32 v156, v153
	v_rcp_iflag_f32_e32 v152, v152
	v_rcp_iflag_f32_e32 v153, v154
	v_rcp_iflag_f32_e32 v154, v155
	v_rcp_iflag_f32_e32 v155, v156
	v_cvt_f32_ubyte3_e32 v157, v148
	v_cvt_f32_ubyte2_e32 v156, v148
	v_cvt_f32_ubyte1_e32 v159, v148
	v_cvt_f32_ubyte0_e32 v158, v148
	v_pk_mul_f32 v[146:147], v[146:147], v[158:159]
	v_pk_mul_f32 v[150:151], v[150:151], v[156:157]
	v_pk_mul_f32 v[38:39], v[38:39], v[146:147]
	v_pk_mul_f32 v[40:41], v[40:41], v[150:151]
	v_cvt_f32_ubyte3_e32 v147, v149
	v_cvt_f32_ubyte2_e32 v146, v149
	v_cvt_f32_ubyte1_e32 v151, v149
	v_cvt_f32_ubyte0_e32 v150, v149
	v_pk_mul_f32 v[148:149], v[152:153], v[150:151]
	v_pk_mul_f32 v[146:147], v[154:155], v[146:147]
	v_pk_mul_f32 v[34:35], v[34:35], v[148:149]
	v_pk_mul_f32 v[36:37], v[36:37], v[146:147]
	s_waitcnt vmcnt(2)
	v_cvt_f32_ubyte0_e32 v0, v142
	v_cvt_f32_ubyte1_e32 v146, v142
	v_cvt_f32_ubyte2_e32 v147, v142
	v_cvt_f32_ubyte3_e32 v148, v142
	v_cvt_f32_ubyte0_e32 v149, v143
	v_cvt_f32_ubyte1_e32 v150, v143
	v_cvt_f32_ubyte2_e32 v151, v143
	v_cvt_f32_ubyte3_e32 v152, v143
	v_rcp_iflag_f32_e32 v142, v0
	v_rcp_iflag_f32_e32 v143, v146
	v_rcp_iflag_f32_e32 v146, v147
	v_rcp_iflag_f32_e32 v147, v148
	v_rcp_iflag_f32_e32 v148, v149
	v_rcp_iflag_f32_e32 v149, v150
	v_rcp_iflag_f32_e32 v150, v151
	v_rcp_iflag_f32_e32 v151, v152
	v_cvt_f32_ubyte3_e32 v153, v138
	v_cvt_f32_ubyte2_e32 v152, v138
	v_cvt_f32_ubyte1_e32 v155, v138
	v_cvt_f32_ubyte0_e32 v154, v138
	v_pk_mul_f32 v[142:143], v[142:143], v[154:155]
	v_pk_mul_f32 v[146:147], v[146:147], v[152:153]
	v_pk_mul_f32 v[30:31], v[30:31], v[142:143]
	v_pk_mul_f32 v[32:33], v[32:33], v[146:147]
	v_cvt_f32_ubyte3_e32 v143, v139
	v_cvt_f32_ubyte2_e32 v142, v139
	v_cvt_f32_ubyte1_e32 v147, v139
	v_cvt_f32_ubyte0_e32 v146, v139
	v_pk_mul_f32 v[138:139], v[148:149], v[146:147]
	v_pk_mul_f32 v[142:143], v[150:151], v[142:143]
	v_pk_mul_f32 v[22:23], v[22:23], v[138:139]
	v_pk_mul_f32 v[24:25], v[24:25], v[142:143]
	v_cvt_f32_ubyte0_e32 v0, v144
	v_cvt_f32_ubyte1_e32 v139, v144
	v_cvt_f32_ubyte2_e32 v142, v144
	v_cvt_f32_ubyte3_e32 v143, v144
	v_rcp_iflag_f32_e32 v138, v0
	v_rcp_iflag_f32_e32 v139, v139
	v_rcp_iflag_f32_e32 v142, v142
	v_rcp_iflag_f32_e32 v143, v143
	v_cvt_f32_ubyte0_e32 v144, v145
	v_cvt_f32_ubyte1_e32 v146, v145
	v_cvt_f32_ubyte2_e32 v147, v145
	v_cvt_f32_ubyte3_e32 v148, v145
	v_rcp_iflag_f32_e32 v144, v144
	v_rcp_iflag_f32_e32 v145, v146
	v_rcp_iflag_f32_e32 v146, v147
	v_rcp_iflag_f32_e32 v147, v148
	v_cvt_f32_ubyte3_e32 v149, v140
	v_cvt_f32_ubyte2_e32 v148, v140
	v_cvt_f32_ubyte1_e32 v151, v140
	v_cvt_f32_ubyte0_e32 v150, v140
	v_pk_mul_f32 v[138:139], v[138:139], v[150:151]
	v_pk_mul_f32 v[142:143], v[142:143], v[148:149]
	v_pk_mul_f32 v[26:27], v[26:27], v[138:139]
	v_pk_mul_f32 v[28:29], v[28:29], v[142:143]
	v_cvt_f32_ubyte3_e32 v139, v141
	v_cvt_f32_ubyte2_e32 v138, v141
	v_cvt_f32_ubyte1_e32 v143, v141
	v_cvt_f32_ubyte0_e32 v142, v141
	v_pk_mul_f32 v[140:141], v[144:145], v[142:143]
	v_pk_mul_f32 v[138:139], v[146:147], v[138:139]
	v_pk_mul_f32 v[18:19], v[18:19], v[140:141]
	v_pk_mul_f32 v[20:21], v[20:21], v[138:139]
	s_waitcnt vmcnt(0)
	v_cvt_f32_ubyte0_e32 v0, v134
	v_cvt_f32_ubyte1_e32 v138, v134
	v_cvt_f32_ubyte2_e32 v139, v134
	v_cvt_f32_ubyte3_e32 v140, v134
	v_cvt_f32_ubyte0_e32 v141, v135
	v_cvt_f32_ubyte1_e32 v142, v135
	v_cvt_f32_ubyte2_e32 v143, v135
	v_cvt_f32_ubyte3_e32 v144, v135
	v_rcp_iflag_f32_e32 v134, v0
	v_rcp_iflag_f32_e32 v135, v138
	v_rcp_iflag_f32_e32 v138, v139
	v_rcp_iflag_f32_e32 v139, v140
	v_rcp_iflag_f32_e32 v140, v141
	v_rcp_iflag_f32_e32 v141, v142
	v_rcp_iflag_f32_e32 v142, v143
	v_rcp_iflag_f32_e32 v143, v144
	v_cvt_f32_ubyte3_e32 v145, v130
	v_cvt_f32_ubyte2_e32 v144, v130
	v_cvt_f32_ubyte1_e32 v147, v130
	v_cvt_f32_ubyte0_e32 v146, v130
	v_pk_mul_f32 v[134:135], v[134:135], v[146:147]
	v_pk_mul_f32 v[138:139], v[138:139], v[144:145]
	v_pk_mul_f32 v[14:15], v[14:15], v[134:135]
	v_pk_mul_f32 v[16:17], v[16:17], v[138:139]
	v_cvt_f32_ubyte3_e32 v135, v131
	v_cvt_f32_ubyte2_e32 v134, v131
	v_cvt_f32_ubyte1_e32 v139, v131
	v_cvt_f32_ubyte0_e32 v138, v131
	v_pk_mul_f32 v[130:131], v[140:141], v[138:139]
	v_pk_mul_f32 v[134:135], v[142:143], v[134:135]
	v_pk_mul_f32 v[6:7], v[6:7], v[130:131]
	v_pk_mul_f32 v[8:9], v[8:9], v[134:135]
	v_cvt_f32_ubyte0_e32 v0, v136
	v_cvt_f32_ubyte1_e32 v131, v136
	v_cvt_f32_ubyte2_e32 v134, v136
	v_cvt_f32_ubyte3_e32 v135, v136
	v_rcp_iflag_f32_e32 v130, v0
	v_rcp_iflag_f32_e32 v131, v131
	v_rcp_iflag_f32_e32 v134, v134
	v_rcp_iflag_f32_e32 v135, v135
	v_cvt_f32_ubyte0_e32 v136, v137
	v_cvt_f32_ubyte1_e32 v138, v137
	v_cvt_f32_ubyte2_e32 v139, v137
	v_cvt_f32_ubyte3_e32 v140, v137
	v_rcp_iflag_f32_e32 v136, v136
	v_rcp_iflag_f32_e32 v137, v138
	v_rcp_iflag_f32_e32 v138, v139
	v_rcp_iflag_f32_e32 v139, v140
	v_cvt_f32_ubyte3_e32 v141, v132
	v_cvt_f32_ubyte2_e32 v140, v132
	v_cvt_f32_ubyte1_e32 v143, v132
	v_cvt_f32_ubyte0_e32 v142, v132
	v_pk_mul_f32 v[130:131], v[130:131], v[142:143]
	v_pk_mul_f32 v[134:135], v[134:135], v[140:141]
	v_pk_mul_f32 v[10:11], v[10:11], v[130:131]
	v_pk_mul_f32 v[12:13], v[12:13], v[134:135]
	v_cvt_f32_ubyte3_e32 v131, v133
	v_cvt_f32_ubyte2_e32 v130, v133
	v_cvt_f32_ubyte1_e32 v135, v133
	v_cvt_f32_ubyte0_e32 v134, v133
	v_pk_mul_f32 v[132:133], v[136:137], v[134:135]
	v_pk_mul_f32 v[130:131], v[138:139], v[130:131]
	v_pk_mul_f32 v[2:3], v[2:3], v[132:133]
	v_pk_mul_f32 v[4:5], v[4:5], v[130:131]

; #define PG8_STAGE(bufoff, gbase, voff) do { _Pragma("unroll") for (int _i = 0; _i < 2; ++_i) \
;         __builtin_amdgcn_global_load_lds((const unsigned*)((const char*)(gbase) + (voff)[_i]), (LAS unsigned*)(lds + (bufoff) + ldsw + _i * 8192), 16, 0, 0); } while (0)
; #define PG8_LDA(dst, b, h) do { _Pragma("unroll") for (int m = 0; m < 4; ++m) _Pragma("unroll") for (int k = 0; k < 2; ++k) dst[m][k] = *(const LAS bf16x8*)(lds + PG8_SA(b, h) + aoffk[k] + m * 2048); } while (0)
; #define PG8_LDB(dst, b, h) do { _Pragma("unroll") for (int n = 0; n < 2; ++n) _Pragma("unroll") for (int k = 0; k < 2; ++k) dst[n][k] = *(const LAS bf16x8*)(lds + PG8_SB(b, h) + boffk[k] + n * 2048); } while (0)
; #define PG8_WAIT_V(n) asm volatile("s_waitcnt vmcnt(" #n ")" ::: "memory")
; #define PG8_WAIT_L(n) asm volatile("s_waitcnt lgkmcnt(" #n ")" ::: "memory")
; #define PG8_BAR __builtin_amdgcn_s_barrier()
; #define PG8_SCHED __builtin_amdgcn_sched_barrier(0)
; template <class Epi, class Sched, class GemmT>
; __device__ __forceinline__ void gemm_phase(LAS unsigned char* lds, const GemmT& g, const Sched& S, const Epi& E, const int wid) {
;     ...
;             for (int t = 0; t < nt; t += 2) {
;                 const bool last = (t == nt - 2);
;                 const char* a1 = cA + (size_t)(t + 1) * kstep;
;                 const char* a2 = last ? ns.A : cA + (size_t)(t + 2) * kstep; const char* b2 = last ? ns.B : cB + (size_t)(t + 2) * kstep;
;                 const char* a3 = a2 + kstep; const char* b3 = b2 + kstep;
;                 unsigned vA2[2], vB2[2];
; #pragma unroll
;                 for (int i = 0; i < 2; ++i) { vA2[i] = last ? nvA[i] : voffA[i]; vB2[i] = last ? nvB[i] : voffB[i]; }
;                 const size_t hA2 = last ? nhA : hstepA, hB2 = last ? nhB : hstepB;
;                 PG8_LDB(B0, 0, 0); PG8_LDB(B1, 0, 1); PG8_SCHED; PG8_LDA(At, 0, 0); PG8_STAGE(PG8_SA(1, 1), a1 + hstepA, voffA);
;                 PG8_WAIT_V(8); PG8_WAIT_L(0); PG8_BAR; PG8_MMA(0, 0, At, B0); PG8_MMA(0, 1, At, B1); PG8_BAR; PG8_SCHED;
;                 PG8_LDA(At, 0, 1); PG8_STAGE(PG8_SB(0, 0), b2, vB2); PG8_STAGE(PG8_SB(0, 1), b2 + hB2, vB2); PG8_STAGE(PG8_SA(0, 0), a2, vA2);
;                 PG8_WAIT_V(8); PG8_WAIT_L(0); PG8_BAR; PG8_MMA(1, 0, At, B0); PG8_MMA(1, 1, At, B1); PG8_BAR; PG8_SCHED;
.LBB0_846:
	ds_read_b128 v[128:131], v194
	ds_read_b128 v[132:135], v195
	ds_read_b128 v[136:139], v196
	ds_read_b128 v[140:143], v197
	ds_read_b128 v[144:147], v198
	ds_read_b128 v[148:151], v199
	ds_read_b128 v[152:155], v200
	ds_read_b128 v[168:171], v201
	s_add_u32 s44, s42, 0xfff00080
	s_addc_u32 s45, s43, -1
	s_cmp_eq_u32 s62, 60
	s_cselect_b32 s51, s37, s45
	s_cselect_b32 s50, s36, s44
	s_cselect_b32 s45, s59, s61
	s_cselect_b32 s44, s41, s60
	s_add_i32 m0, s14, 0xc000
	ds_read_b128 v[172:175], v202
	ds_read_b128 v[176:179], v202 offset:2048
	ds_read_b128 v[180:183], v203
	ds_read_b128 v[184:187], v203 offset:2048
	ds_read_b128 v[208:211], v202 offset:4096
	ds_read_b128 v[212:215], v202 offset:6144
	ds_read_b128 v[216:219], v203 offset:4096
	ds_read_b128 v[220:223], v203 offset:6144
	global_load_lds_dwordx4 v156, s[42:43]
	s_add_i32 m0, s14, 0xe000
	s_nop 0
	global_load_lds_dwordx4 v160, s[42:43]
	s_waitcnt vmcnt(8)
	s_waitcnt lgkmcnt(0)
	s_waitcnt lgkmcnt(0)
	v_mfma_f32_16x16x32_bf16 v[124:127], v[128:131], v[172:175], v[124:127]
	v_mfma_f32_16x16x32_bf16 v[124:127], v[132:135], v[180:183], v[124:127]
	v_mfma_f32_16x16x32_bf16 v[120:123], v[140:143], v[180:183], v[120:123]
	v_mfma_f32_16x16x32_bf16 v[120:123], v[136:139], v[172:175], v[120:123]
	s_barrier
	s_setprio 3
	v_mfma_f32_16x16x32_bf16 v[104:107], v[136:139], v[176:179], v[104:107]
	v_mfma_f32_16x16x32_bf16 v[104:107], v[140:143], v[184:187], v[104:107]
	v_mfma_f32_16x16x32_bf16 v[108:111], v[132:135], v[184:187], v[108:111]
	v_mfma_f32_16x16x32_bf16 v[108:111], v[128:131], v[176:179], v[108:111]
	v_mfma_f32_16x16x32_bf16 v[92:95], v[128:131], v[208:211], v[92:95]
	v_mfma_f32_16x16x32_bf16 v[92:95], v[132:135], v[216:219], v[92:95]
	v_mfma_f32_16x16x32_bf16 v[88:91], v[140:143], v[216:219], v[88:91]
	v_mfma_f32_16x16x32_bf16 v[88:91], v[136:139], v[208:211], v[88:91]
	v_mfma_f32_16x16x32_bf16 v[72:75], v[136:139], v[212:215], v[72:75]
	v_mfma_f32_16x16x32_bf16 v[72:75], v[140:143], v[220:223], v[72:75]
	v_mfma_f32_16x16x32_bf16 v[76:79], v[132:135], v[220:223], v[76:79]
	v_mfma_f32_16x16x32_bf16 v[76:79], v[128:131], v[212:215], v[76:79]
	s_setprio 0
	s_setprio 3
	v_mfma_f32_16x16x32_bf16 v[116:119], v[144:147], v[172:175], v[116:119]
	v_mfma_f32_16x16x32_bf16 v[116:119], v[148:151], v[180:183], v[116:119]
	v_mfma_f32_16x16x32_bf16 v[112:115], v[168:171], v[180:183], v[112:115]
	v_mfma_f32_16x16x32_bf16 v[112:115], v[152:155], v[172:175], v[112:115]
	v_mfma_f32_16x16x32_bf16 v[96:99], v[152:155], v[176:179], v[96:99]
	v_mfma_f32_16x16x32_bf16 v[96:99], v[168:171], v[184:187], v[96:99]
	v_mfma_f32_16x16x32_bf16 v[100:103], v[148:151], v[184:187], v[100:103]
	v_mfma_f32_16x16x32_bf16 v[100:103], v[144:147], v[176:179], v[100:103]
	v_mfma_f32_16x16x32_bf16 v[84:87], v[144:147], v[208:211], v[84:87]
	v_mfma_f32_16x16x32_bf16 v[84:87], v[148:151], v[216:219], v[84:87]
	v_mfma_f32_16x16x32_bf16 v[80:83], v[168:171], v[216:219], v[80:83]
	v_mfma_f32_16x16x32_bf16 v[80:83], v[152:155], v[208:211], v[80:83]
	v_mfma_f32_16x16x32_bf16 v[64:67], v[152:155], v[212:215], v[64:67]
	v_mfma_f32_16x16x32_bf16 v[64:67], v[168:171], v[220:223], v[64:67]
	v_mfma_f32_16x16x32_bf16 v[68:71], v[148:151], v[220:223], v[68:71]
	v_mfma_f32_16x16x32_bf16 v[68:71], v[144:147], v[212:215], v[68:71]
	s_setprio 0
	s_barrier
	s_add_i32 s48, s54, s68
	s_mov_b32 m0, s48
	ds_read_b128 v[172:175], v202 offset:16384
	ds_read_b128 v[176:179], v202 offset:18432
	ds_read_b128 v[180:183], v203 offset:16384
	ds_read_b128 v[184:187], v203 offset:18432
	ds_read_b128 v[208:211], v202 offset:20480
	ds_read_b128 v[212:215], v202 offset:22528
	ds_read_b128 v[216:219], v203 offset:20480
	ds_read_b128 v[220:223], v203 offset:22528
	global_load_lds_dwordx4 v158, s[44:45]
	s_add_i32 m0, s48, 0x2000
	s_add_u32 s48, s44, 0x100000
	s_addc_u32 s49, s45, 0
	s_add_i32 s63, s55, s68
	global_load_lds_dwordx4 v162, s[44:45]
	s_mov_b32 m0, s63
	s_nop 0
	global_load_lds_dwordx4 v158, s[48:49]
	s_add_i32 m0, s63, 0x2000
	s_nop 0
	global_load_lds_dwordx4 v162, s[48:49]
	s_mov_b32 m0, s14
	s_nop 0
	global_load_lds_dwordx4 v156, s[50:51]
	s_mov_b32 m0, s15
	s_nop 0
	global_load_lds_dwordx4 v160, s[50:51]
	s_waitcnt vmcnt(8)
	s_waitcnt lgkmcnt(0)
	s_waitcnt lgkmcnt(0)
	v_mfma_f32_16x16x32_bf16 v[52:55], v[128:131], v[172:175], v[52:55]
	v_mfma_f32_16x16x32_bf16 v[52:55], v[132:135], v[180:183], v[52:55]
	v_mfma_f32_16x16x32_bf16 v[48:51], v[140:143], v[180:183], v[48:51]
	v_mfma_f32_16x16x32_bf16 v[48:51], v[136:139], v[172:175], v[48:51]
	s_barrier
	s_setprio 3
	v_mfma_f32_16x16x32_bf16 v[32:35], v[136:139], v[176:179], v[32:35]
	v_mfma_f32_16x16x32_bf16 v[32:35], v[140:143], v[184:187], v[32:35]
	v_mfma_f32_16x16x32_bf16 v[36:39], v[132:135], v[184:187], v[36:39]
	v_mfma_f32_16x16x32_bf16 v[36:39], v[128:131], v[176:179], v[36:39]
	v_mfma_f32_16x16x32_bf16 v[20:23], v[128:131], v[208:211], v[20:23]
	v_mfma_f32_16x16x32_bf16 v[20:23], v[132:135], v[216:219], v[20:23]
	v_mfma_f32_16x16x32_bf16 v[16:19], v[140:143], v[216:219], v[16:19]
	v_mfma_f32_16x16x32_bf16 v[16:19], v[136:139], v[208:211], v[16:19]
	v_mfma_f32_16x16x32_bf16 v[0:3], v[136:139], v[212:215], v[0:3]
	v_mfma_f32_16x16x32_bf16 v[0:3], v[140:143], v[220:223], v[0:3]
	v_mfma_f32_16x16x32_bf16 v[4:7], v[132:135], v[220:223], v[4:7]
	v_mfma_f32_16x16x32_bf16 v[4:7], v[128:131], v[212:215], v[4:7]
	s_setprio 0
	s_setprio 3
	v_mfma_f32_16x16x32_bf16 v[60:63], v[144:147], v[172:175], v[60:63]
	v_mfma_f32_16x16x32_bf16 v[60:63], v[148:151], v[180:183], v[60:63]
	v_mfma_f32_16x16x32_bf16 v[56:59], v[168:171], v[180:183], v[56:59]
	v_mfma_f32_16x16x32_bf16 v[56:59], v[152:155], v[172:175], v[56:59]
	v_mfma_f32_16x16x32_bf16 v[40:43], v[152:155], v[176:179], v[40:43]
	v_mfma_f32_16x16x32_bf16 v[40:43], v[168:171], v[184:187], v[40:43]
	v_mfma_f32_16x16x32_bf16 v[44:47], v[148:151], v[184:187], v[44:47]
	v_mfma_f32_16x16x32_bf16 v[44:47], v[144:147], v[176:179], v[44:47]
	v_mfma_f32_16x16x32_bf16 v[28:31], v[144:147], v[208:211], v[28:31]
	v_mfma_f32_16x16x32_bf16 v[28:31], v[148:151], v[216:219], v[28:31]
	v_mfma_f32_16x16x32_bf16 v[24:27], v[168:171], v[216:219], v[24:27]
	v_mfma_f32_16x16x32_bf16 v[24:27], v[152:155], v[208:211], v[24:27]
	v_mfma_f32_16x16x32_bf16 v[8:11], v[152:155], v[212:215], v[8:11]
	v_mfma_f32_16x16x32_bf16 v[8:11], v[168:171], v[220:223], v[8:11]
	v_mfma_f32_16x16x32_bf16 v[12:15], v[148:151], v[220:223], v[12:15]
	v_mfma_f32_16x16x32_bf16 v[12:15], v[144:147], v[212:215], v[12:15]
	s_setprio 0
	s_barrier
; #define PG8_STAGE(bufoff, gbase, voff) do { _Pragma("unroll") for (int _i = 0; _i < 2; ++_i) \
;         __builtin_amdgcn_global_load_lds((const unsigned*)((const char*)(gbase) + (voff)[_i]), (LAS unsigned*)(lds + (bufoff) + ldsw + _i * 8192), 16, 0, 0); } while (0)
; #define PG8_LDA(dst, b, h) do { _Pragma("unroll") for (int m = 0; m < 4; ++m) _Pragma("unroll") for (int k = 0; k < 2; ++k) dst[m][k] = *(const LAS bf16x8*)(lds + PG8_SA(b, h) + aoffk[k] + m * 2048); } while (0)
; #define PG8_LDB(dst, b, h) do { _Pragma("unroll") for (int n = 0; n < 2; ++n) _Pragma("unroll") for (int k = 0; k < 2; ++k) dst[n][k] = *(const LAS bf16x8*)(lds + PG8_SB(b, h) + boffk[k] + n * 2048); } while (0)
; #define PG8_WAIT_V(n) asm volatile("s_waitcnt vmcnt(" #n ")" ::: "memory")
; #define PG8_WAIT_L(n) asm volatile("s_waitcnt lgkmcnt(" #n ")" ::: "memory")
; #define PG8_BAR __builtin_amdgcn_s_barrier()
; #define PG8_SCHED __builtin_amdgcn_sched_barrier(0)
; template <class Epi, class Sched, class GemmT>
; __device__ __forceinline__ void gemm_phase(LAS unsigned char* lds, const GemmT& g, const Sched& S, const Epi& E, const int wid) {
;     ...
;                 PG8_LDB(B0, 1, 0); PG8_LDB(B1, 1, 1); PG8_SCHED; PG8_LDA(At, 1, 0); PG8_STAGE(PG8_SA(0, 1), a2 + hA2, vA2);
;                 PG8_WAIT_V(8); PG8_WAIT_L(0); PG8_BAR; PG8_MMA(0, 0, At, B0); PG8_MMA(0, 1, At, B1); PG8_BAR; PG8_SCHED;
;                 PG8_LDA(At, 1, 1); PG8_STAGE(PG8_SB(1, 0), b3, vB2); PG8_STAGE(PG8_SB(1, 1), b3 + hB2, vB2); PG8_STAGE(PG8_SA(1, 0), a3, vA2);
;                 PG8_WAIT_V(8); PG8_WAIT_L(0); PG8_BAR; PG8_MMA(1, 0, At, B0); PG8_MMA(1, 1, At, B1); PG8_BAR; PG8_SCHED;
;             }
	s_add_i32 s63, 0, 0x18000
	s_add_i32 s64, 0, 0x1c000
	ds_read_b128 v[128:131], v188
	ds_read_b128 v[132:135], v189
	ds_read_b128 v[136:139], v204
	ds_read_b128 v[140:143], v205
	ds_read_b128 v[144:147], v224
	ds_read_b128 v[148:151], v225
	ds_read_b128 v[152:155], v206
	ds_read_b128 v[168:171], v207
	s_add_u32 s48, s50, 0x100000
	s_addc_u32 s49, s51, 0
	s_mov_b32 m0, s22
	ds_read_b128 v[172:175], v202 offset:32768
	ds_read_b128 v[176:179], v202 offset:34816
	ds_read_b128 v[180:183], v203 offset:32768
	ds_read_b128 v[184:187], v203 offset:34816
	ds_read_b128 v[208:211], v202 offset:36864
	ds_read_b128 v[212:215], v202 offset:38912
	ds_read_b128 v[216:219], v203 offset:36864
	ds_read_b128 v[220:223], v203 offset:38912
	global_load_lds_dwordx4 v156, s[48:49]
	s_mov_b32 m0, s23
	s_nop 0
	global_load_lds_dwordx4 v160, s[48:49]
	s_waitcnt vmcnt(8)
	s_waitcnt lgkmcnt(0)
	s_waitcnt lgkmcnt(0)
	v_mfma_f32_16x16x32_bf16 v[124:127], v[128:131], v[172:175], v[124:127]
	v_mfma_f32_16x16x32_bf16 v[124:127], v[132:135], v[180:183], v[124:127]
	v_mfma_f32_16x16x32_bf16 v[120:123], v[140:143], v[180:183], v[120:123]
	v_mfma_f32_16x16x32_bf16 v[120:123], v[136:139], v[172:175], v[120:123]
	s_barrier
	s_setprio 3
	v_mfma_f32_16x16x32_bf16 v[104:107], v[136:139], v[176:179], v[104:107]
	v_mfma_f32_16x16x32_bf16 v[104:107], v[140:143], v[184:187], v[104:107]
	v_mfma_f32_16x16x32_bf16 v[108:111], v[132:135], v[184:187], v[108:111]
	v_mfma_f32_16x16x32_bf16 v[108:111], v[128:131], v[176:179], v[108:111]
	v_mfma_f32_16x16x32_bf16 v[92:95], v[128:131], v[208:211], v[92:95]
	v_mfma_f32_16x16x32_bf16 v[92:95], v[132:135], v[216:219], v[92:95]
	v_mfma_f32_16x16x32_bf16 v[88:91], v[140:143], v[216:219], v[88:91]
	v_mfma_f32_16x16x32_bf16 v[88:91], v[136:139], v[208:211], v[88:91]
	v_mfma_f32_16x16x32_bf16 v[72:75], v[136:139], v[212:215], v[72:75]
	v_mfma_f32_16x16x32_bf16 v[72:75], v[140:143], v[220:223], v[72:75]
	v_mfma_f32_16x16x32_bf16 v[76:79], v[132:135], v[220:223], v[76:79]
	v_mfma_f32_16x16x32_bf16 v[76:79], v[128:131], v[212:215], v[76:79]
	s_setprio 0
	s_setprio 3
	v_mfma_f32_16x16x32_bf16 v[116:119], v[144:147], v[172:175], v[116:119]
	v_mfma_f32_16x16x32_bf16 v[116:119], v[148:151], v[180:183], v[116:119]
	v_mfma_f32_16x16x32_bf16 v[112:115], v[168:171], v[180:183], v[112:115]
	v_mfma_f32_16x16x32_bf16 v[112:115], v[152:155], v[172:175], v[112:115]
	v_mfma_f32_16x16x32_bf16 v[96:99], v[152:155], v[176:179], v[96:99]
	v_mfma_f32_16x16x32_bf16 v[96:99], v[168:171], v[184:187], v[96:99]
	v_mfma_f32_16x16x32_bf16 v[100:103], v[148:151], v[184:187], v[100:103]
	v_mfma_f32_16x16x32_bf16 v[100:103], v[144:147], v[176:179], v[100:103]
	v_mfma_f32_16x16x32_bf16 v[84:87], v[144:147], v[208:211], v[84:87]
	v_mfma_f32_16x16x32_bf16 v[84:87], v[148:151], v[216:219], v[84:87]
	v_mfma_f32_16x16x32_bf16 v[80:83], v[168:171], v[216:219], v[80:83]
	v_mfma_f32_16x16x32_bf16 v[80:83], v[152:155], v[208:211], v[80:83]
	v_mfma_f32_16x16x32_bf16 v[64:67], v[152:155], v[212:215], v[64:67]
	v_mfma_f32_16x16x32_bf16 v[64:67], v[168:171], v[220:223], v[64:67]
	v_mfma_f32_16x16x32_bf16 v[68:71], v[148:151], v[220:223], v[68:71]
	v_mfma_f32_16x16x32_bf16 v[68:71], v[144:147], v[212:215], v[68:71]
	s_setprio 0
	s_barrier
	s_add_i32 s48, s63, s68
	s_mov_b32 m0, s48
	ds_read_b128 v[172:175], v202 offset:49152
	ds_read_b128 v[176:179], v202 offset:51200
	ds_read_b128 v[180:183], v203 offset:49152
	ds_read_b128 v[184:187], v203 offset:51200
	ds_read_b128 v[208:211], v202 offset:53248
	ds_read_b128 v[212:215], v202 offset:55296
	ds_read_b128 v[216:219], v203 offset:53248
	ds_read_b128 v[220:223], v203 offset:55296
	s_add_u32 s98, s44, 0x80
	s_addc_u32 s99, s45, 0
	s_nop 0
	global_load_lds_dwordx4 v158, s[98:99]
	s_add_i32 m0, s48, 0x2000
	s_add_u32 s44, s44, 0x100080
	s_addc_u32 s45, s45, 0
	s_add_i32 s48, s64, s68
	global_load_lds_dwordx4 v162, s[98:99]
	s_mov_b32 m0, s48
	s_nop 0
	global_load_lds_dwordx4 v158, s[44:45]
	s_add_i32 m0, s48, 0x2000
	s_nop 0
	global_load_lds_dwordx4 v162, s[44:45]
	s_mov_b32 m0, s34
	s_nop 0
	s_add_u32 s98, s50, 0x80
	s_addc_u32 s99, s51, 0
	s_nop 0
	global_load_lds_dwordx4 v156, s[98:99]
	s_mov_b32 m0, s35
	s_nop 0
	global_load_lds_dwordx4 v160, s[98:99]
	s_waitcnt vmcnt(8)
	s_waitcnt lgkmcnt(0)
	s_waitcnt lgkmcnt(0)
	v_mfma_f32_16x16x32_bf16 v[52:55], v[128:131], v[172:175], v[52:55]
	v_mfma_f32_16x16x32_bf16 v[52:55], v[132:135], v[180:183], v[52:55]
	v_mfma_f32_16x16x32_bf16 v[48:51], v[140:143], v[180:183], v[48:51]
	v_mfma_f32_16x16x32_bf16 v[48:51], v[136:139], v[172:175], v[48:51]
	s_barrier
	s_setprio 3
	v_mfma_f32_16x16x32_bf16 v[32:35], v[136:139], v[176:179], v[32:35]
	v_mfma_f32_16x16x32_bf16 v[32:35], v[140:143], v[184:187], v[32:35]
	v_mfma_f32_16x16x32_bf16 v[36:39], v[132:135], v[184:187], v[36:39]
	v_mfma_f32_16x16x32_bf16 v[36:39], v[128:131], v[176:179], v[36:39]
	v_mfma_f32_16x16x32_bf16 v[20:23], v[128:131], v[208:211], v[20:23]
	v_mfma_f32_16x16x32_bf16 v[20:23], v[132:135], v[216:219], v[20:23]
	v_mfma_f32_16x16x32_bf16 v[16:19], v[140:143], v[216:219], v[16:19]
	v_mfma_f32_16x16x32_bf16 v[16:19], v[136:139], v[208:211], v[16:19]
	v_mfma_f32_16x16x32_bf16 v[0:3], v[136:139], v[212:215], v[0:3]
	v_mfma_f32_16x16x32_bf16 v[0:3], v[140:143], v[220:223], v[0:3]
	v_mfma_f32_16x16x32_bf16 v[4:7], v[132:135], v[220:223], v[4:7]
	v_mfma_f32_16x16x32_bf16 v[4:7], v[128:131], v[212:215], v[4:7]
	s_setprio 0
	s_setprio 3
	v_mfma_f32_16x16x32_bf16 v[60:63], v[144:147], v[172:175], v[60:63]
	v_mfma_f32_16x16x32_bf16 v[60:63], v[148:151], v[180:183], v[60:63]
	v_mfma_f32_16x16x32_bf16 v[56:59], v[168:171], v[180:183], v[56:59]
	v_mfma_f32_16x16x32_bf16 v[56:59], v[152:155], v[172:175], v[56:59]
	v_mfma_f32_16x16x32_bf16 v[40:43], v[152:155], v[176:179], v[40:43]
	v_mfma_f32_16x16x32_bf16 v[40:43], v[168:171], v[184:187], v[40:43]
	v_mfma_f32_16x16x32_bf16 v[44:47], v[148:151], v[184:187], v[44:47]
	v_mfma_f32_16x16x32_bf16 v[44:47], v[144:147], v[176:179], v[44:47]
	v_mfma_f32_16x16x32_bf16 v[28:31], v[144:147], v[208:211], v[28:31]
	v_mfma_f32_16x16x32_bf16 v[28:31], v[148:151], v[216:219], v[28:31]
	v_mfma_f32_16x16x32_bf16 v[24:27], v[168:171], v[216:219], v[24:27]
	v_mfma_f32_16x16x32_bf16 v[24:27], v[152:155], v[208:211], v[24:27]
	v_mfma_f32_16x16x32_bf16 v[8:11], v[152:155], v[212:215], v[8:11]
	v_mfma_f32_16x16x32_bf16 v[8:11], v[168:171], v[220:223], v[8:11]
	v_mfma_f32_16x16x32_bf16 v[12:15], v[148:151], v[220:223], v[12:15]
	v_mfma_f32_16x16x32_bf16 v[12:15], v[144:147], v[212:215], v[12:15]
	s_setprio 0
	s_add_i32 s62, s62, 2
	s_add_u32 s42, s42, 0x100
	s_addc_u32 s43, s43, 0
	s_add_u32 s60, s60, 0x100
	s_addc_u32 s61, s61, 0
	s_cmp_gt_u32 s62, 61
	s_barrier
	s_cbranch_scc0 .LBB0_846
	s_and_b64 vcc, exec, s[20:21]
	s_cbranch_vccz .LBB0_849
	s_barrier

; #define PG8_STAGE(bufoff, gbase, voff) do { _Pragma("unroll") for (int _i = 0; _i < 2; ++_i) \
;         __builtin_amdgcn_global_load_lds((const unsigned*)((const char*)(gbase) + (voff)[_i]), (LAS unsigned*)(lds + (bufoff) + ldsw + _i * 8192), 16, 0, 0); } while (0)
; #define PG8_LDA(dst, b, h) do { _Pragma("unroll") for (int m = 0; m < 4; ++m) _Pragma("unroll") for (int k = 0; k < 2; ++k) dst[m][k] = *(const LAS bf16x8*)(lds + PG8_SA(b, h) + aoffk[k] + m * 2048); } while (0)
; #define PG8_LDB(dst, b, h) do { _Pragma("unroll") for (int n = 0; n < 2; ++n) _Pragma("unroll") for (int k = 0; k < 2; ++k) dst[n][k] = *(const LAS bf16x8*)(lds + PG8_SB(b, h) + boffk[k] + n * 2048); } while (0)
; #define PG8_WAIT_V(n) asm volatile("s_waitcnt vmcnt(" #n ")" ::: "memory")
; #define PG8_WAIT_L(n) asm volatile("s_waitcnt lgkmcnt(" #n ")" ::: "memory")
; #define PG8_BAR __builtin_amdgcn_s_barrier()
; #define PG8_SCHED __builtin_amdgcn_sched_barrier(0)
; template <class Epi, class Sched, class GemmT>
; __device__ __forceinline__ void gemm_phase(LAS unsigned char* lds, const GemmT& g, const Sched& S, const Epi& E, const int wid) {
;     ...
;             for (int t = 0; t < nt; t += 2) {
;                 const bool last = (t == nt - 2);
;                 const char* a1 = cA + (size_t)(t + 1) * kstep;
;                 const char* a2 = last ? ns.A : cA + (size_t)(t + 2) * kstep; const char* b2 = last ? ns.B : cB + (size_t)(t + 2) * kstep;
;                 const char* a3 = a2 + kstep; const char* b3 = b2 + kstep;
;                 unsigned vA2[2], vB2[2];
; #pragma unroll
;                 for (int i = 0; i < 2; ++i) { vA2[i] = last ? nvA[i] : voffA[i]; vB2[i] = last ? nvB[i] : voffB[i]; }
;                 const size_t hA2 = last ? nhA : hstepA, hB2 = last ? nhB : hstepB;
;                 PG8_LDB(B0, 0, 0); PG8_LDB(B1, 0, 1); PG8_SCHED; PG8_LDA(At, 0, 0); PG8_STAGE(PG8_SA(1, 1), a1 + hstepA, voffA);
;                 PG8_WAIT_V(8); PG8_WAIT_L(0); PG8_BAR; PG8_MMA(0, 0, At, B0); PG8_MMA(0, 1, At, B1); PG8_BAR; PG8_SCHED;
;                 PG8_LDA(At, 0, 1); PG8_STAGE(PG8_SB(0, 0), b2, vB2); PG8_STAGE(PG8_SB(0, 1), b2 + hB2, vB2); PG8_STAGE(PG8_SA(0, 0), a2, vA2);
;                 PG8_WAIT_V(8); PG8_WAIT_L(0); PG8_BAR; PG8_MMA(1, 0, At, B0); PG8_MMA(1, 1, At, B1); PG8_BAR; PG8_SCHED;
.LBB0_936:
	ds_read_b128 v[12:15], v223
	ds_read_b128 v[132:135], v224
	ds_read_b128 v[136:139], v225
	ds_read_b128 v[140:143], v226
	ds_read_b128 v[144:147], v227
	ds_read_b128 v[148:151], v229
	ds_read_b128 v[152:155], v230
	ds_read_b128 v[156:159], v231
	s_add_u32 s66, s64, 0xfff00080
	s_addc_u32 s67, s65, -1
	s_cmp_eq_u32 s81, 60
	s_cselect_b32 s71, s57, s67
	s_cselect_b32 s70, s56, s66
	s_cselect_b32 s67, s77, s79
	s_cselect_b32 s66, s63, s78
	s_add_i32 m0, s14, 0xc000
	ds_read_b128 v[160:163], v232
	ds_read_b128 v[164:167], v232 offset:2048
	ds_read_b128 v[168:171], v233
	ds_read_b128 v[172:175], v233 offset:2048
	ds_read_b128 v[188:191], v232 offset:4096
	ds_read_b128 v[192:195], v232 offset:6144
	ds_read_b128 v[196:199], v233 offset:4096
	ds_read_b128 v[200:203], v233 offset:6144
	global_load_lds_dwordx4 v176, s[64:65]
	s_add_i32 m0, s14, 0xe000
	s_nop 0
	global_load_lds_dwordx4 v180, s[64:65]
	s_waitcnt vmcnt(8)
	s_waitcnt lgkmcnt(0)
	s_waitcnt lgkmcnt(0)
	v_mfma_f32_16x16x32_bf16 v[124:127], v[12:15], v[160:163], v[124:127]
	v_mfma_f32_16x16x32_bf16 v[124:127], v[132:135], v[168:171], v[124:127]
	v_mfma_f32_16x16x32_bf16 v[120:123], v[140:143], v[168:171], v[120:123]
	v_mfma_f32_16x16x32_bf16 v[120:123], v[136:139], v[160:163], v[120:123]
	s_barrier
	s_setprio 3
	v_mfma_f32_16x16x32_bf16 v[104:107], v[136:139], v[164:167], v[104:107]
	v_mfma_f32_16x16x32_bf16 v[104:107], v[140:143], v[172:175], v[104:107]
	v_mfma_f32_16x16x32_bf16 v[40:43], v[132:135], v[172:175], v[40:43]
	v_mfma_f32_16x16x32_bf16 v[40:43], v[12:15], v[164:167], v[40:43]
	v_mfma_f32_16x16x32_bf16 v[32:35], v[12:15], v[188:191], v[32:35]
	v_mfma_f32_16x16x32_bf16 v[32:35], v[132:135], v[196:199], v[32:35]
	v_mfma_f32_16x16x32_bf16 v[96:99], v[140:143], v[196:199], v[96:99]
	v_mfma_f32_16x16x32_bf16 v[96:99], v[136:139], v[188:191], v[96:99]
	v_mfma_f32_16x16x32_bf16 v[92:95], v[136:139], v[192:195], v[92:95]
	v_mfma_f32_16x16x32_bf16 v[92:95], v[140:143], v[200:203], v[92:95]
	v_mfma_f32_16x16x32_bf16 v[112:115], v[132:135], v[200:203], v[112:115]
	v_mfma_f32_16x16x32_bf16 v[112:115], v[12:15], v[192:195], v[112:115]
	s_setprio 0
	s_setprio 3
	v_mfma_f32_16x16x32_bf16 v[68:71], v[144:147], v[160:163], v[68:71]
	v_mfma_f32_16x16x32_bf16 v[68:71], v[148:151], v[168:171], v[68:71]
	v_mfma_f32_16x16x32_bf16 v[60:63], v[156:159], v[168:171], v[60:63]
	v_mfma_f32_16x16x32_bf16 v[60:63], v[152:155], v[160:163], v[60:63]
	v_mfma_f32_16x16x32_bf16 v[20:23], v[152:155], v[164:167], v[20:23]
	v_mfma_f32_16x16x32_bf16 v[20:23], v[156:159], v[172:175], v[20:23]
	v_mfma_f32_16x16x32_bf16 v[76:79], v[148:151], v[172:175], v[76:79]
	v_mfma_f32_16x16x32_bf16 v[76:79], v[144:147], v[164:167], v[76:79]
	v_mfma_f32_16x16x32_bf16 v[72:75], v[144:147], v[188:191], v[72:75]
	v_mfma_f32_16x16x32_bf16 v[72:75], v[148:151], v[196:199], v[72:75]
	v_mfma_f32_16x16x32_bf16 v[16:19], v[156:159], v[196:199], v[16:19]
	v_mfma_f32_16x16x32_bf16 v[16:19], v[152:155], v[188:191], v[16:19]
	v_mfma_f32_16x16x32_bf16 v[80:83], v[152:155], v[192:195], v[80:83]
	v_mfma_f32_16x16x32_bf16 v[80:83], v[156:159], v[200:203], v[80:83]
	v_mfma_f32_16x16x32_bf16 v[84:87], v[148:151], v[200:203], v[84:87]
	v_mfma_f32_16x16x32_bf16 v[84:87], v[144:147], v[192:195], v[84:87]
	s_setprio 0
	s_barrier
	s_add_i32 s80, s69, s68
	s_mov_b32 m0, s80
	ds_read_b128 v[160:163], v232 offset:16384
	ds_read_b128 v[164:167], v232 offset:18432
	ds_read_b128 v[168:171], v233 offset:16384
	ds_read_b128 v[172:175], v233 offset:18432
	ds_read_b128 v[188:191], v232 offset:20480
	ds_read_b128 v[192:195], v232 offset:22528
	ds_read_b128 v[196:199], v233 offset:20480
	ds_read_b128 v[200:203], v233 offset:22528
	global_load_lds_dwordx4 v178, s[66:67]
	s_add_i32 m0, s80, 0x2000
	s_add_u32 s82, s66, 0x100000
	s_addc_u32 s83, s67, 0
	s_add_i32 s80, s72, s68
	global_load_lds_dwordx4 v182, s[66:67]
	s_mov_b32 m0, s80
	s_nop 0
	global_load_lds_dwordx4 v178, s[82:83]
	s_add_i32 m0, s80, 0x2000
	s_nop 0
	global_load_lds_dwordx4 v182, s[82:83]
	s_mov_b32 m0, s14
	s_nop 0
	s_add_u32 s100, s70, 0x80
	s_addc_u32 s101, s71, 0
	global_load_lds_dwordx4 v176, s[70:71]
	s_mov_b32 m0, s15
	s_nop 0
	global_load_lds_dwordx4 v180, s[70:71]
	s_waitcnt vmcnt(8)
	s_waitcnt lgkmcnt(0)
	s_waitcnt lgkmcnt(0)
	v_mfma_f32_16x16x32_bf16 v[56:59], v[12:15], v[160:163], v[56:59]
	v_mfma_f32_16x16x32_bf16 v[56:59], v[132:135], v[168:171], v[56:59]
	v_mfma_f32_16x16x32_bf16 v[108:111], v[136:139], v[160:163], v[108:111]
	v_mfma_f32_16x16x32_bf16 v[108:111], v[140:143], v[168:171], v[108:111]
	s_barrier
	s_setprio 3
	v_mfma_f32_16x16x32_bf16 v[36:39], v[12:15], v[164:167], v[36:39]
	v_mfma_f32_16x16x32_bf16 v[36:39], v[132:135], v[172:175], v[36:39]
	v_mfma_f32_16x16x32_bf16 v[100:103], v[136:139], v[164:167], v[100:103]
	v_mfma_f32_16x16x32_bf16 v[100:103], v[140:143], v[172:175], v[100:103]
	v_mfma_f32_16x16x32_bf16 v[28:31], v[12:15], v[188:191], v[28:31]
	v_mfma_f32_16x16x32_bf16 v[28:31], v[132:135], v[196:199], v[28:31]
	v_mfma_f32_16x16x32_bf16 v[88:91], v[136:139], v[188:191], v[88:91]
	v_mfma_f32_16x16x32_bf16 v[88:91], v[140:143], v[196:199], v[88:91]
	v_mfma_f32_16x16x32_bf16 v[24:27], v[136:139], v[192:195], v[24:27]
	v_mfma_f32_16x16x32_bf16 v[24:27], v[140:143], v[200:203], v[24:27]
	v_mfma_f32_16x16x32_bf16 v[12:15], v[12:15], v[192:195], v[64:67]
	v_mfma_f32_16x16x32_bf16 v[12:15], v[132:135], v[200:203], v[12:15]
	s_setprio 0
	s_setprio 3
	v_mfma_f32_16x16x32_bf16 v[64:67], v[144:147], v[192:195], v[116:119]
	v_mfma_f32_16x16x32_bf16 v[116:119], v[148:151], v[200:203], v[64:67]
	v_mfma_f32_16x16x32_bf16 v[44:47], v[144:147], v[160:163], v[44:47]
	v_mfma_f32_16x16x32_bf16 v[44:47], v[148:151], v[168:171], v[44:47]
	v_mfma_f32_16x16x32_bf16 v[0:3], v[152:155], v[160:163], v[0:3]
	v_mfma_f32_16x16x32_bf16 v[0:3], v[156:159], v[168:171], v[0:3]
	v_mfma_f32_16x16x32_bf16 v[48:51], v[144:147], v[164:167], v[48:51]
	v_mfma_f32_16x16x32_bf16 v[48:51], v[148:151], v[172:175], v[48:51]
	v_mfma_f32_16x16x32_bf16 v[4:7], v[152:155], v[164:167], v[4:7]
	v_mfma_f32_16x16x32_bf16 v[4:7], v[156:159], v[172:175], v[4:7]
	v_mfma_f32_16x16x32_bf16 v[64:67], v[152:155], v[192:195], v[128:131]
	v_mfma_f32_16x16x32_bf16 v[128:131], v[156:159], v[200:203], v[64:67]
	v_mfma_f32_16x16x32_bf16 v[52:55], v[144:147], v[188:191], v[52:55]
	v_mfma_f32_16x16x32_bf16 v[52:55], v[148:151], v[196:199], v[52:55]
	v_mfma_f32_16x16x32_bf16 v[8:11], v[152:155], v[188:191], v[8:11]
	v_mfma_f32_16x16x32_bf16 v[8:11], v[156:159], v[196:199], v[8:11]
	s_setprio 0
	s_barrier
; #define PG8_STAGE(bufoff, gbase, voff) do { _Pragma("unroll") for (int _i = 0; _i < 2; ++_i) \
;         __builtin_amdgcn_global_load_lds((const unsigned*)((const char*)(gbase) + (voff)[_i]), (LAS unsigned*)(lds + (bufoff) + ldsw + _i * 8192), 16, 0, 0); } while (0)
; #define PG8_LDA(dst, b, h) do { _Pragma("unroll") for (int m = 0; m < 4; ++m) _Pragma("unroll") for (int k = 0; k < 2; ++k) dst[m][k] = *(const LAS bf16x8*)(lds + PG8_SA(b, h) + aoffk[k] + m * 2048); } while (0)
; #define PG8_LDB(dst, b, h) do { _Pragma("unroll") for (int n = 0; n < 2; ++n) _Pragma("unroll") for (int k = 0; k < 2; ++k) dst[n][k] = *(const LAS bf16x8*)(lds + PG8_SB(b, h) + boffk[k] + n * 2048); } while (0)
; #define PG8_WAIT_V(n) asm volatile("s_waitcnt vmcnt(" #n ")" ::: "memory")
; #define PG8_WAIT_L(n) asm volatile("s_waitcnt lgkmcnt(" #n ")" ::: "memory")
; #define PG8_BAR __builtin_amdgcn_s_barrier()
; #define PG8_SCHED __builtin_amdgcn_sched_barrier(0)
; template <class Epi, class Sched, class GemmT>
; __device__ __forceinline__ void gemm_phase(LAS unsigned char* lds, const GemmT& g, const Sched& S, const Epi& E, const int wid) {
;     ...
;                 PG8_LDB(B0, 1, 0); PG8_LDB(B1, 1, 1); PG8_SCHED; PG8_LDA(At, 1, 0); PG8_STAGE(PG8_SA(0, 1), a2 + hA2, vA2);
;                 PG8_WAIT_V(8); PG8_WAIT_L(0); PG8_BAR; PG8_MMA(0, 0, At, B0); PG8_MMA(0, 1, At, B1); PG8_BAR; PG8_SCHED;
;                 PG8_LDA(At, 1, 1); PG8_STAGE(PG8_SB(1, 0), b3, vB2); PG8_STAGE(PG8_SB(1, 1), b3 + hB2, vB2); PG8_STAGE(PG8_SA(1, 0), a3, vA2);
;                 PG8_WAIT_V(8); PG8_WAIT_L(0); PG8_BAR; PG8_MMA(1, 0, At, B0); PG8_MMA(1, 1, At, B1); PG8_BAR; PG8_SCHED;
;             }
	s_add_i32 s80, 0, 0x18000
	s_add_i32 s82, 0, 0x1c000
	ds_read_b128 v[64:67], v204
	ds_read_b128 v[132:135], v205
	ds_read_b128 v[136:139], v234
	ds_read_b128 v[140:143], v235
	ds_read_b128 v[144:147], v206
	ds_read_b128 v[148:151], v207
	ds_read_b128 v[152:155], v236
	ds_read_b128 v[156:159], v237
	s_add_u32 s70, s70, 0x100000
	s_addc_u32 s71, s71, 0
	s_mov_b32 m0, s23
	ds_read_b128 v[160:163], v232 offset:32768
	ds_read_b128 v[164:167], v232 offset:34816
	ds_read_b128 v[168:171], v233 offset:32768
	ds_read_b128 v[172:175], v233 offset:34816
	ds_read_b128 v[188:191], v232 offset:36864
	ds_read_b128 v[192:195], v232 offset:38912
	ds_read_b128 v[196:199], v233 offset:36864
	ds_read_b128 v[200:203], v233 offset:38912
	global_load_lds_dwordx4 v176, s[70:71]
	s_mov_b32 m0, s34
	s_nop 0
	global_load_lds_dwordx4 v180, s[70:71]
	s_waitcnt vmcnt(8)
	s_waitcnt lgkmcnt(0)
	s_waitcnt lgkmcnt(0)
	v_mfma_f32_16x16x32_bf16 v[124:127], v[64:67], v[160:163], v[124:127]
	v_mfma_f32_16x16x32_bf16 v[124:127], v[132:135], v[168:171], v[124:127]
	v_mfma_f32_16x16x32_bf16 v[120:123], v[140:143], v[168:171], v[120:123]
	v_mfma_f32_16x16x32_bf16 v[120:123], v[136:139], v[160:163], v[120:123]
	s_barrier
	s_setprio 3
	v_mfma_f32_16x16x32_bf16 v[104:107], v[136:139], v[164:167], v[104:107]
	v_mfma_f32_16x16x32_bf16 v[104:107], v[140:143], v[172:175], v[104:107]
	v_mfma_f32_16x16x32_bf16 v[40:43], v[132:135], v[172:175], v[40:43]
	v_mfma_f32_16x16x32_bf16 v[40:43], v[64:67], v[164:167], v[40:43]
	v_mfma_f32_16x16x32_bf16 v[32:35], v[64:67], v[188:191], v[32:35]
	v_mfma_f32_16x16x32_bf16 v[32:35], v[132:135], v[196:199], v[32:35]
	v_mfma_f32_16x16x32_bf16 v[96:99], v[140:143], v[196:199], v[96:99]
	v_mfma_f32_16x16x32_bf16 v[96:99], v[136:139], v[188:191], v[96:99]
	v_mfma_f32_16x16x32_bf16 v[92:95], v[136:139], v[192:195], v[92:95]
	v_mfma_f32_16x16x32_bf16 v[92:95], v[140:143], v[200:203], v[92:95]
	v_mfma_f32_16x16x32_bf16 v[112:115], v[132:135], v[200:203], v[112:115]
	v_mfma_f32_16x16x32_bf16 v[112:115], v[64:67], v[192:195], v[112:115]
	s_setprio 0
	s_setprio 3
	v_mfma_f32_16x16x32_bf16 v[68:71], v[144:147], v[160:163], v[68:71]
	v_mfma_f32_16x16x32_bf16 v[68:71], v[148:151], v[168:171], v[68:71]
	v_mfma_f32_16x16x32_bf16 v[60:63], v[156:159], v[168:171], v[60:63]
	v_mfma_f32_16x16x32_bf16 v[60:63], v[152:155], v[160:163], v[60:63]
	v_mfma_f32_16x16x32_bf16 v[20:23], v[152:155], v[164:167], v[20:23]
	v_mfma_f32_16x16x32_bf16 v[20:23], v[156:159], v[172:175], v[20:23]
	v_mfma_f32_16x16x32_bf16 v[76:79], v[148:151], v[172:175], v[76:79]
	v_mfma_f32_16x16x32_bf16 v[76:79], v[144:147], v[164:167], v[76:79]
	v_mfma_f32_16x16x32_bf16 v[72:75], v[144:147], v[188:191], v[72:75]
	v_mfma_f32_16x16x32_bf16 v[72:75], v[148:151], v[196:199], v[72:75]
	v_mfma_f32_16x16x32_bf16 v[16:19], v[156:159], v[196:199], v[16:19]
	v_mfma_f32_16x16x32_bf16 v[16:19], v[152:155], v[188:191], v[16:19]
	v_mfma_f32_16x16x32_bf16 v[80:83], v[152:155], v[192:195], v[80:83]
	v_mfma_f32_16x16x32_bf16 v[80:83], v[156:159], v[200:203], v[80:83]
	v_mfma_f32_16x16x32_bf16 v[84:87], v[148:151], v[200:203], v[84:87]
	v_mfma_f32_16x16x32_bf16 v[84:87], v[144:147], v[192:195], v[84:87]
	s_setprio 0
	s_barrier
	s_add_i32 s70, s80, s68
	s_mov_b32 m0, s70
	ds_read_b128 v[160:163], v232 offset:49152
	ds_read_b128 v[164:167], v232 offset:51200
	ds_read_b128 v[168:171], v233 offset:49152
	ds_read_b128 v[172:175], v233 offset:51200
	ds_read_b128 v[188:191], v232 offset:53248
	ds_read_b128 v[192:195], v232 offset:55296
	ds_read_b128 v[196:199], v233 offset:53248
	ds_read_b128 v[200:203], v233 offset:55296
	s_add_u32 s98, s66, 0x80
	s_addc_u32 s99, s67, 0
	s_nop 0
	global_load_lds_dwordx4 v178, s[98:99]
	s_add_i32 m0, s70, 0x2000
	s_add_u32 s66, s66, 0x100080
	s_addc_u32 s67, s67, 0
	s_add_i32 s70, s82, s68
	global_load_lds_dwordx4 v182, s[98:99]
	s_mov_b32 m0, s70
	s_nop 0
	global_load_lds_dwordx4 v178, s[66:67]
	s_add_i32 m0, s70, 0x2000
	s_nop 0
	global_load_lds_dwordx4 v182, s[66:67]
	s_mov_b32 m0, s54
	s_nop 0
	global_load_lds_dwordx4 v176, s[100:101]
	s_mov_b32 m0, s55
	s_nop 0
	global_load_lds_dwordx4 v180, s[100:101]
	s_waitcnt vmcnt(8)
	s_waitcnt lgkmcnt(0)
	s_waitcnt lgkmcnt(0)
	v_mfma_f32_16x16x32_bf16 v[12:15], v[64:67], v[192:195], v[12:15]
	v_mfma_f32_16x16x32_bf16 v[56:59], v[64:67], v[160:163], v[56:59]
	v_mfma_f32_16x16x32_bf16 v[56:59], v[132:135], v[168:171], v[56:59]
	v_mfma_f32_16x16x32_bf16 v[108:111], v[136:139], v[160:163], v[108:111]
	s_barrier
	s_setprio 3
	v_mfma_f32_16x16x32_bf16 v[108:111], v[140:143], v[168:171], v[108:111]
	v_mfma_f32_16x16x32_bf16 v[36:39], v[64:67], v[164:167], v[36:39]
	v_mfma_f32_16x16x32_bf16 v[36:39], v[132:135], v[172:175], v[36:39]
	v_mfma_f32_16x16x32_bf16 v[100:103], v[136:139], v[164:167], v[100:103]
	v_mfma_f32_16x16x32_bf16 v[100:103], v[140:143], v[172:175], v[100:103]
	v_mfma_f32_16x16x32_bf16 v[28:31], v[64:67], v[188:191], v[28:31]
	v_mfma_f32_16x16x32_bf16 v[28:31], v[132:135], v[196:199], v[28:31]
	v_mfma_f32_16x16x32_bf16 v[88:91], v[136:139], v[188:191], v[88:91]
	v_mfma_f32_16x16x32_bf16 v[88:91], v[140:143], v[196:199], v[88:91]
	v_mfma_f32_16x16x32_bf16 v[64:67], v[132:135], v[200:203], v[12:15]
	v_mfma_f32_16x16x32_bf16 v[12:15], v[136:139], v[192:195], v[24:27]
	v_mfma_f32_16x16x32_bf16 v[24:27], v[140:143], v[200:203], v[12:15]
	s_setprio 0
	s_setprio 3
	v_mfma_f32_16x16x32_bf16 v[12:15], v[144:147], v[160:163], v[44:47]
	v_mfma_f32_16x16x32_bf16 v[44:47], v[148:151], v[168:171], v[12:15]
	v_mfma_f32_16x16x32_bf16 v[0:3], v[152:155], v[160:163], v[0:3]
	v_mfma_f32_16x16x32_bf16 v[0:3], v[156:159], v[168:171], v[0:3]
	v_mfma_f32_16x16x32_bf16 v[4:7], v[152:155], v[164:167], v[4:7]
	v_mfma_f32_16x16x32_bf16 v[4:7], v[156:159], v[172:175], v[4:7]
	v_mfma_f32_16x16x32_bf16 v[12:15], v[144:147], v[164:167], v[48:51]
	v_mfma_f32_16x16x32_bf16 v[48:51], v[148:151], v[172:175], v[12:15]
	v_mfma_f32_16x16x32_bf16 v[8:11], v[152:155], v[188:191], v[8:11]
	v_mfma_f32_16x16x32_bf16 v[8:11], v[156:159], v[196:199], v[8:11]
	v_mfma_f32_16x16x32_bf16 v[12:15], v[144:147], v[188:191], v[52:55]
	v_mfma_f32_16x16x32_bf16 v[52:55], v[148:151], v[196:199], v[12:15]
	v_mfma_f32_16x16x32_bf16 v[12:15], v[144:147], v[192:195], v[116:119]
	v_mfma_f32_16x16x32_bf16 v[116:119], v[148:151], v[200:203], v[12:15]
	v_mfma_f32_16x16x32_bf16 v[12:15], v[152:155], v[192:195], v[128:131]
	v_mfma_f32_16x16x32_bf16 v[128:131], v[156:159], v[200:203], v[12:15]
	s_setprio 0
	s_add_i32 s81, s81, 2
	s_add_u32 s64, s64, 0x100
	s_addc_u32 s65, s65, 0
	s_add_u32 s78, s78, 0x100
	s_addc_u32 s79, s79, 0
	s_cmp_gt_u32 s81, 61
	s_barrier
	s_cbranch_scc0 .LBB0_936
	s_and_b64 vcc, exec, s[40:41]
	s_cbranch_vccz .LBB0_939
	s_barrier

; #define PG8_STAGE(bufoff, gbase, voff) do { _Pragma("unroll") for (int _i = 0; _i < 2; ++_i) \
;         __builtin_amdgcn_global_load_lds((const unsigned*)((const char*)(gbase) + (voff)[_i]), (LAS unsigned*)(lds + (bufoff) + ldsw + _i * 8192), 16, 0, 0); } while (0)
; #define PG8_LDA(dst, b, h) do { _Pragma("unroll") for (int m = 0; m < 4; ++m) _Pragma("unroll") for (int k = 0; k < 2; ++k) dst[m][k] = *(const LAS bf16x8*)(lds + PG8_SA(b, h) + aoffk[k] + m * 2048); } while (0)
; #define PG8_LDB(dst, b, h) do { _Pragma("unroll") for (int n = 0; n < 2; ++n) _Pragma("unroll") for (int k = 0; k < 2; ++k) dst[n][k] = *(const LAS bf16x8*)(lds + PG8_SB(b, h) + boffk[k] + n * 2048); } while (0)
; #define PG8_WAIT_V(n) asm volatile("s_waitcnt vmcnt(" #n ")" ::: "memory")
; #define PG8_WAIT_L(n) asm volatile("s_waitcnt lgkmcnt(" #n ")" ::: "memory")
; #define PG8_BAR __builtin_amdgcn_s_barrier()
; #define PG8_SCHED __builtin_amdgcn_sched_barrier(0)
; template <class Epi, class Sched, class GemmT>
; __device__ __forceinline__ void gemm_phase(LAS unsigned char* lds, const GemmT& g, const Sched& S, const Epi& E, const int wid) {
;     ...
;             for (int t = 0; t < nt; t += 2) {
;                 const bool last = (t == nt - 2);
;                 const char* a1 = cA + (size_t)(t + 1) * kstep;
;                 const char* a2 = last ? ns.A : cA + (size_t)(t + 2) * kstep; const char* b2 = last ? ns.B : cB + (size_t)(t + 2) * kstep;
;                 const char* a3 = a2 + kstep; const char* b3 = b2 + kstep;
;                 unsigned vA2[2], vB2[2];
; #pragma unroll
;                 for (int i = 0; i < 2; ++i) { vA2[i] = last ? nvA[i] : voffA[i]; vB2[i] = last ? nvB[i] : voffB[i]; }
;                 const size_t hA2 = last ? nhA : hstepA, hB2 = last ? nhB : hstepB;
;                 PG8_LDB(B0, 0, 0); PG8_LDB(B1, 0, 1); PG8_SCHED; PG8_LDA(At, 0, 0); PG8_STAGE(PG8_SA(1, 1), a1 + hstepA, voffA);
;                 PG8_WAIT_V(8); PG8_WAIT_L(0); PG8_BAR; PG8_MMA(0, 0, At, B0); PG8_MMA(0, 1, At, B1); PG8_BAR; PG8_SCHED;
;                 PG8_LDA(At, 0, 1); PG8_STAGE(PG8_SB(0, 0), b2, vB2); PG8_STAGE(PG8_SB(0, 1), b2 + hB2, vB2); PG8_STAGE(PG8_SA(0, 0), a2, vA2);
;                 PG8_WAIT_V(8); PG8_WAIT_L(0); PG8_BAR; PG8_MMA(1, 0, At, B0); PG8_MMA(1, 1, At, B1); PG8_BAR; PG8_SCHED;
.LBB0_1096:
	ds_read_b128 v[128:131], v188
	ds_read_b128 v[132:135], v189
	ds_read_b128 v[136:139], v190
	ds_read_b128 v[140:143], v191
	ds_read_b128 v[144:147], v192
	ds_read_b128 v[148:151], v193
	ds_read_b128 v[152:155], v194
	ds_read_b128 v[156:159], v195
	s_add_u32 s24, s22, 0xffd50080
	s_addc_u32 s25, s23, -1
	s_cmpk_eq_i32 s56, 0xa8
	s_cselect_b32 s27, s19, s25
	s_cselect_b32 s26, s18, s24
	s_cselect_b32 s25, s53, s55
	s_cselect_b32 s24, s52, s54
	s_add_i32 m0, s34, 0xc000
	ds_read_b128 v[160:163], v196
	ds_read_b128 v[164:167], v196 offset:2048
	ds_read_b128 v[180:183], v197
	ds_read_b128 v[202:205], v197 offset:2048
	ds_read_b128 v[206:209], v196 offset:4096
	ds_read_b128 v[210:213], v196 offset:6144
	ds_read_b128 v[214:217], v197 offset:4096
	ds_read_b128 v[218:221], v197 offset:6144
	global_load_lds_dwordx4 v168, s[22:23]
	s_add_i32 m0, s34, 0xe000
	s_nop 0
	global_load_lds_dwordx4 v172, s[22:23]
	s_waitcnt vmcnt(8)
	s_waitcnt lgkmcnt(0)
	s_waitcnt lgkmcnt(0)
	v_mfma_f32_16x16x32_bf16 v[124:127], v[128:131], v[160:163], v[124:127]
	v_mfma_f32_16x16x32_bf16 v[124:127], v[132:135], v[180:183], v[124:127]
	v_mfma_f32_16x16x32_bf16 v[120:123], v[140:143], v[180:183], v[120:123]
	v_mfma_f32_16x16x32_bf16 v[120:123], v[136:139], v[160:163], v[120:123]
	s_barrier
	s_setprio 3
	v_mfma_f32_16x16x32_bf16 v[104:107], v[136:139], v[164:167], v[104:107]
	v_mfma_f32_16x16x32_bf16 v[104:107], v[140:143], v[202:205], v[104:107]
	v_mfma_f32_16x16x32_bf16 v[112:115], v[132:135], v[202:205], v[112:115]
	v_mfma_f32_16x16x32_bf16 v[112:115], v[128:131], v[164:167], v[112:115]
	v_mfma_f32_16x16x32_bf16 v[96:99], v[128:131], v[206:209], v[96:99]
	v_mfma_f32_16x16x32_bf16 v[96:99], v[132:135], v[214:217], v[96:99]
	v_mfma_f32_16x16x32_bf16 v[88:91], v[140:143], v[214:217], v[88:91]
	v_mfma_f32_16x16x32_bf16 v[88:91], v[136:139], v[206:209], v[88:91]
	v_mfma_f32_16x16x32_bf16 v[72:75], v[136:139], v[210:213], v[72:75]
	v_mfma_f32_16x16x32_bf16 v[72:75], v[140:143], v[218:221], v[72:75]
	v_mfma_f32_16x16x32_bf16 v[80:83], v[132:135], v[218:221], v[80:83]
	v_mfma_f32_16x16x32_bf16 v[80:83], v[128:131], v[210:213], v[80:83]
	s_setprio 0
	s_setprio 3
	v_mfma_f32_16x16x32_bf16 v[116:119], v[144:147], v[160:163], v[116:119]
	v_mfma_f32_16x16x32_bf16 v[116:119], v[148:151], v[180:183], v[116:119]
	v_mfma_f32_16x16x32_bf16 v[108:111], v[156:159], v[180:183], v[108:111]
	v_mfma_f32_16x16x32_bf16 v[108:111], v[152:155], v[160:163], v[108:111]
	v_mfma_f32_16x16x32_bf16 v[92:95], v[152:155], v[164:167], v[92:95]
	v_mfma_f32_16x16x32_bf16 v[92:95], v[156:159], v[202:205], v[92:95]
	v_mfma_f32_16x16x32_bf16 v[100:103], v[148:151], v[202:205], v[100:103]
	v_mfma_f32_16x16x32_bf16 v[100:103], v[144:147], v[164:167], v[100:103]
	v_mfma_f32_16x16x32_bf16 v[84:87], v[144:147], v[206:209], v[84:87]
	v_mfma_f32_16x16x32_bf16 v[84:87], v[148:151], v[214:217], v[84:87]
	v_mfma_f32_16x16x32_bf16 v[76:79], v[156:159], v[214:217], v[76:79]
	v_mfma_f32_16x16x32_bf16 v[76:79], v[152:155], v[206:209], v[76:79]
	v_mfma_f32_16x16x32_bf16 v[60:63], v[152:155], v[210:213], v[60:63]
	v_mfma_f32_16x16x32_bf16 v[60:63], v[156:159], v[218:221], v[60:63]
	v_mfma_f32_16x16x32_bf16 v[68:71], v[148:151], v[218:221], v[68:71]
	v_mfma_f32_16x16x32_bf16 v[68:71], v[144:147], v[210:213], v[68:71]
	s_setprio 0
	s_barrier
	s_add_i32 s57, s41, s68
	s_mov_b32 m0, s57
	ds_read_b128 v[160:163], v196 offset:16384
	ds_read_b128 v[164:167], v196 offset:18432
	ds_read_b128 v[180:183], v197 offset:16384
	ds_read_b128 v[202:205], v197 offset:18432
	ds_read_b128 v[206:209], v196 offset:20480
	ds_read_b128 v[210:213], v196 offset:22528
	ds_read_b128 v[214:217], v197 offset:20480
	ds_read_b128 v[218:221], v197 offset:22528
	global_load_lds_dwordx4 v170, s[24:25]
	s_add_i32 m0, s57, 0x2000
	s_add_u32 s58, s24, 0x2b0000
	s_addc_u32 s59, s25, 0
	s_add_i32 s57, s42, s68
	global_load_lds_dwordx4 v174, s[24:25]
	s_mov_b32 m0, s57
	s_nop 0
	global_load_lds_dwordx4 v170, s[58:59]
	s_add_i32 m0, s57, 0x2000
	s_nop 0
	global_load_lds_dwordx4 v174, s[58:59]
	s_mov_b32 m0, s34
	s_nop 0
	s_add_u32 s100, s26, 0x80
	s_addc_u32 s101, s27, 0
	global_load_lds_dwordx4 v168, s[26:27]
	s_mov_b32 m0, s35
	s_nop 0
	global_load_lds_dwordx4 v172, s[26:27]
	s_waitcnt vmcnt(8)
	s_waitcnt lgkmcnt(0)
	s_waitcnt lgkmcnt(0)
	v_mfma_f32_16x16x32_bf16 v[52:55], v[128:131], v[160:163], v[52:55]
	v_mfma_f32_16x16x32_bf16 v[52:55], v[132:135], v[180:183], v[52:55]
	v_mfma_f32_16x16x32_bf16 v[48:51], v[140:143], v[180:183], v[48:51]
	v_mfma_f32_16x16x32_bf16 v[48:51], v[136:139], v[160:163], v[48:51]
	s_barrier
	s_setprio 3
	v_mfma_f32_16x16x32_bf16 v[32:35], v[136:139], v[164:167], v[32:35]
	v_mfma_f32_16x16x32_bf16 v[32:35], v[140:143], v[202:205], v[32:35]
	v_mfma_f32_16x16x32_bf16 v[36:39], v[132:135], v[202:205], v[36:39]
	v_mfma_f32_16x16x32_bf16 v[36:39], v[128:131], v[164:167], v[36:39]
	v_mfma_f32_16x16x32_bf16 v[20:23], v[128:131], v[206:209], v[20:23]
	v_mfma_f32_16x16x32_bf16 v[20:23], v[132:135], v[214:217], v[20:23]
	v_mfma_f32_16x16x32_bf16 v[8:11], v[140:143], v[214:217], v[8:11]
	v_mfma_f32_16x16x32_bf16 v[8:11], v[136:139], v[206:209], v[8:11]
	v_mfma_f32_16x16x32_bf16 v[0:3], v[136:139], v[210:213], v[0:3]
	v_mfma_f32_16x16x32_bf16 v[0:3], v[140:143], v[218:221], v[0:3]
	v_mfma_f32_16x16x32_bf16 v[4:7], v[132:135], v[218:221], v[4:7]
	v_mfma_f32_16x16x32_bf16 v[4:7], v[128:131], v[210:213], v[4:7]
	s_setprio 0
	s_setprio 3
	v_mfma_f32_16x16x32_bf16 v[64:67], v[144:147], v[160:163], v[64:67]
	v_mfma_f32_16x16x32_bf16 v[64:67], v[148:151], v[180:183], v[64:67]
	v_mfma_f32_16x16x32_bf16 v[56:59], v[156:159], v[180:183], v[56:59]
	v_mfma_f32_16x16x32_bf16 v[56:59], v[152:155], v[160:163], v[56:59]
	v_mfma_f32_16x16x32_bf16 v[40:43], v[152:155], v[164:167], v[40:43]
	v_mfma_f32_16x16x32_bf16 v[40:43], v[156:159], v[202:205], v[40:43]
	v_mfma_f32_16x16x32_bf16 v[44:47], v[148:151], v[202:205], v[44:47]
	v_mfma_f32_16x16x32_bf16 v[44:47], v[144:147], v[164:167], v[44:47]
	v_mfma_f32_16x16x32_bf16 v[28:31], v[144:147], v[206:209], v[28:31]
	v_mfma_f32_16x16x32_bf16 v[28:31], v[148:151], v[214:217], v[28:31]
	v_mfma_f32_16x16x32_bf16 v[24:27], v[156:159], v[214:217], v[24:27]
	v_mfma_f32_16x16x32_bf16 v[24:27], v[152:155], v[206:209], v[24:27]
	v_mfma_f32_16x16x32_bf16 v[12:15], v[152:155], v[210:213], v[12:15]
	v_mfma_f32_16x16x32_bf16 v[12:15], v[156:159], v[218:221], v[12:15]
	v_mfma_f32_16x16x32_bf16 v[16:19], v[148:151], v[218:221], v[16:19]
	v_mfma_f32_16x16x32_bf16 v[16:19], v[144:147], v[210:213], v[16:19]
	s_setprio 0
	s_barrier
; #define PG8_STAGE(bufoff, gbase, voff) do { _Pragma("unroll") for (int _i = 0; _i < 2; ++_i) \
;         __builtin_amdgcn_global_load_lds((const unsigned*)((const char*)(gbase) + (voff)[_i]), (LAS unsigned*)(lds + (bufoff) + ldsw + _i * 8192), 16, 0, 0); } while (0)
; #define PG8_LDA(dst, b, h) do { _Pragma("unroll") for (int m = 0; m < 4; ++m) _Pragma("unroll") for (int k = 0; k < 2; ++k) dst[m][k] = *(const LAS bf16x8*)(lds + PG8_SA(b, h) + aoffk[k] + m * 2048); } while (0)
; #define PG8_LDB(dst, b, h) do { _Pragma("unroll") for (int n = 0; n < 2; ++n) _Pragma("unroll") for (int k = 0; k < 2; ++k) dst[n][k] = *(const LAS bf16x8*)(lds + PG8_SB(b, h) + boffk[k] + n * 2048); } while (0)
; #define PG8_WAIT_V(n) asm volatile("s_waitcnt vmcnt(" #n ")" ::: "memory")
; #define PG8_WAIT_L(n) asm volatile("s_waitcnt lgkmcnt(" #n ")" ::: "memory")
; #define PG8_BAR __builtin_amdgcn_s_barrier()
; #define PG8_SCHED __builtin_amdgcn_sched_barrier(0)
; template <class Epi, class Sched, class GemmT>
; __device__ __forceinline__ void gemm_phase(LAS unsigned char* lds, const GemmT& g, const Sched& S, const Epi& E, const int wid) {
;     ...
;                 PG8_LDB(B0, 1, 0); PG8_LDB(B1, 1, 1); PG8_SCHED; PG8_LDA(At, 1, 0); PG8_STAGE(PG8_SA(0, 1), a2 + hA2, vA2);
;                 PG8_WAIT_V(8); PG8_WAIT_L(0); PG8_BAR; PG8_MMA(0, 0, At, B0); PG8_MMA(0, 1, At, B1); PG8_BAR; PG8_SCHED;
;                 PG8_LDA(At, 1, 1); PG8_STAGE(PG8_SB(1, 0), b3, vB2); PG8_STAGE(PG8_SB(1, 1), b3 + hB2, vB2); PG8_STAGE(PG8_SA(1, 0), a3, vA2);
;                 PG8_WAIT_V(8); PG8_WAIT_L(0); PG8_BAR; PG8_MMA(1, 0, At, B0); PG8_MMA(1, 1, At, B1); PG8_BAR; PG8_SCHED;
;             }
	s_add_i32 s57, 0, 0x18000
	s_add_i32 s58, 0, 0x1c000
	ds_read_b128 v[128:131], v222
	ds_read_b128 v[132:135], v223
	ds_read_b128 v[136:139], v198
	ds_read_b128 v[140:143], v199
	ds_read_b128 v[144:147], v224
	ds_read_b128 v[148:151], v225
	ds_read_b128 v[152:155], v200
	ds_read_b128 v[156:159], v201
	s_add_u32 s26, s26, 0x2b0000
	s_addc_u32 s27, s27, 0
	s_mov_b32 m0, s36
	ds_read_b128 v[160:163], v196 offset:32768
	ds_read_b128 v[164:167], v196 offset:34816
	ds_read_b128 v[180:183], v197 offset:32768
	ds_read_b128 v[202:205], v197 offset:34816
	ds_read_b128 v[206:209], v196 offset:36864
	ds_read_b128 v[210:213], v196 offset:38912
	ds_read_b128 v[214:217], v197 offset:36864
	ds_read_b128 v[218:221], v197 offset:38912
	global_load_lds_dwordx4 v168, s[26:27]
	s_mov_b32 m0, s37
	s_nop 0
	global_load_lds_dwordx4 v172, s[26:27]
	s_waitcnt vmcnt(8)
	s_waitcnt lgkmcnt(0)
	s_waitcnt lgkmcnt(0)
	v_mfma_f32_16x16x32_bf16 v[124:127], v[128:131], v[160:163], v[124:127]
	v_mfma_f32_16x16x32_bf16 v[124:127], v[132:135], v[180:183], v[124:127]
	v_mfma_f32_16x16x32_bf16 v[120:123], v[140:143], v[180:183], v[120:123]
	v_mfma_f32_16x16x32_bf16 v[120:123], v[136:139], v[160:163], v[120:123]
	s_barrier
	s_setprio 3
	v_mfma_f32_16x16x32_bf16 v[104:107], v[136:139], v[164:167], v[104:107]
	v_mfma_f32_16x16x32_bf16 v[104:107], v[140:143], v[202:205], v[104:107]
	v_mfma_f32_16x16x32_bf16 v[112:115], v[132:135], v[202:205], v[112:115]
	v_mfma_f32_16x16x32_bf16 v[112:115], v[128:131], v[164:167], v[112:115]
	v_mfma_f32_16x16x32_bf16 v[96:99], v[128:131], v[206:209], v[96:99]
	v_mfma_f32_16x16x32_bf16 v[96:99], v[132:135], v[214:217], v[96:99]
	v_mfma_f32_16x16x32_bf16 v[88:91], v[140:143], v[214:217], v[88:91]
	v_mfma_f32_16x16x32_bf16 v[88:91], v[136:139], v[206:209], v[88:91]
	v_mfma_f32_16x16x32_bf16 v[72:75], v[136:139], v[210:213], v[72:75]
	v_mfma_f32_16x16x32_bf16 v[72:75], v[140:143], v[218:221], v[72:75]
	v_mfma_f32_16x16x32_bf16 v[80:83], v[132:135], v[218:221], v[80:83]
	v_mfma_f32_16x16x32_bf16 v[80:83], v[128:131], v[210:213], v[80:83]
	s_setprio 0
	s_setprio 3
	v_mfma_f32_16x16x32_bf16 v[116:119], v[144:147], v[160:163], v[116:119]
	v_mfma_f32_16x16x32_bf16 v[116:119], v[148:151], v[180:183], v[116:119]
	v_mfma_f32_16x16x32_bf16 v[108:111], v[156:159], v[180:183], v[108:111]
	v_mfma_f32_16x16x32_bf16 v[108:111], v[152:155], v[160:163], v[108:111]
	v_mfma_f32_16x16x32_bf16 v[92:95], v[152:155], v[164:167], v[92:95]
	v_mfma_f32_16x16x32_bf16 v[92:95], v[156:159], v[202:205], v[92:95]
	v_mfma_f32_16x16x32_bf16 v[100:103], v[148:151], v[202:205], v[100:103]
	v_mfma_f32_16x16x32_bf16 v[100:103], v[144:147], v[164:167], v[100:103]
	v_mfma_f32_16x16x32_bf16 v[84:87], v[144:147], v[206:209], v[84:87]
	v_mfma_f32_16x16x32_bf16 v[84:87], v[148:151], v[214:217], v[84:87]
	v_mfma_f32_16x16x32_bf16 v[76:79], v[156:159], v[214:217], v[76:79]
	v_mfma_f32_16x16x32_bf16 v[76:79], v[152:155], v[206:209], v[76:79]
	v_mfma_f32_16x16x32_bf16 v[60:63], v[152:155], v[210:213], v[60:63]
	v_mfma_f32_16x16x32_bf16 v[60:63], v[156:159], v[218:221], v[60:63]
	v_mfma_f32_16x16x32_bf16 v[68:71], v[148:151], v[218:221], v[68:71]
	v_mfma_f32_16x16x32_bf16 v[68:71], v[144:147], v[210:213], v[68:71]
	s_setprio 0
	s_barrier
	s_add_i32 s26, s57, s68
	s_mov_b32 m0, s26
	ds_read_b128 v[160:163], v196 offset:49152
	ds_read_b128 v[164:167], v196 offset:51200
	ds_read_b128 v[180:183], v197 offset:49152
	ds_read_b128 v[202:205], v197 offset:51200
	ds_read_b128 v[206:209], v196 offset:53248
	ds_read_b128 v[210:213], v196 offset:55296
	ds_read_b128 v[214:217], v197 offset:53248
	ds_read_b128 v[218:221], v197 offset:55296
	s_add_u32 s98, s24, 0x80
	s_addc_u32 s99, s25, 0
	s_nop 0
	global_load_lds_dwordx4 v170, s[98:99]
	s_add_i32 m0, s26, 0x2000
	s_add_u32 s24, s24, 0x2b0080
	s_addc_u32 s25, s25, 0
	s_add_i32 s26, s58, s68
	global_load_lds_dwordx4 v174, s[98:99]
	s_mov_b32 m0, s26
	s_nop 0
	global_load_lds_dwordx4 v170, s[24:25]
	s_add_i32 m0, s26, 0x2000
	s_nop 0
	global_load_lds_dwordx4 v174, s[24:25]
	s_mov_b32 m0, s39
	s_nop 0
	global_load_lds_dwordx4 v168, s[100:101]
	s_mov_b32 m0, s40
	s_nop 0
	global_load_lds_dwordx4 v172, s[100:101]
	s_waitcnt vmcnt(8)
	s_waitcnt lgkmcnt(0)
	s_waitcnt lgkmcnt(0)
	v_mfma_f32_16x16x32_bf16 v[52:55], v[128:131], v[160:163], v[52:55]
	v_mfma_f32_16x16x32_bf16 v[52:55], v[132:135], v[180:183], v[52:55]
	v_mfma_f32_16x16x32_bf16 v[48:51], v[140:143], v[180:183], v[48:51]
	v_mfma_f32_16x16x32_bf16 v[48:51], v[136:139], v[160:163], v[48:51]
	s_barrier
	s_setprio 3
	v_mfma_f32_16x16x32_bf16 v[32:35], v[136:139], v[164:167], v[32:35]
	v_mfma_f32_16x16x32_bf16 v[32:35], v[140:143], v[202:205], v[32:35]
	v_mfma_f32_16x16x32_bf16 v[36:39], v[132:135], v[202:205], v[36:39]
	v_mfma_f32_16x16x32_bf16 v[36:39], v[128:131], v[164:167], v[36:39]
	v_mfma_f32_16x16x32_bf16 v[20:23], v[128:131], v[206:209], v[20:23]
	v_mfma_f32_16x16x32_bf16 v[20:23], v[132:135], v[214:217], v[20:23]
	v_mfma_f32_16x16x32_bf16 v[8:11], v[140:143], v[214:217], v[8:11]
	v_mfma_f32_16x16x32_bf16 v[8:11], v[136:139], v[206:209], v[8:11]
	v_mfma_f32_16x16x32_bf16 v[0:3], v[136:139], v[210:213], v[0:3]
	v_mfma_f32_16x16x32_bf16 v[0:3], v[140:143], v[218:221], v[0:3]
	v_mfma_f32_16x16x32_bf16 v[4:7], v[132:135], v[218:221], v[4:7]
	v_mfma_f32_16x16x32_bf16 v[4:7], v[128:131], v[210:213], v[4:7]
	s_setprio 0
	s_setprio 3
	v_mfma_f32_16x16x32_bf16 v[64:67], v[144:147], v[160:163], v[64:67]
	v_mfma_f32_16x16x32_bf16 v[64:67], v[148:151], v[180:183], v[64:67]
	v_mfma_f32_16x16x32_bf16 v[56:59], v[156:159], v[180:183], v[56:59]
	v_mfma_f32_16x16x32_bf16 v[56:59], v[152:155], v[160:163], v[56:59]
	v_mfma_f32_16x16x32_bf16 v[40:43], v[152:155], v[164:167], v[40:43]
	v_mfma_f32_16x16x32_bf16 v[40:43], v[156:159], v[202:205], v[40:43]
	v_mfma_f32_16x16x32_bf16 v[44:47], v[148:151], v[202:205], v[44:47]
	v_mfma_f32_16x16x32_bf16 v[44:47], v[144:147], v[164:167], v[44:47]
	v_mfma_f32_16x16x32_bf16 v[28:31], v[144:147], v[206:209], v[28:31]
	v_mfma_f32_16x16x32_bf16 v[28:31], v[148:151], v[214:217], v[28:31]
	v_mfma_f32_16x16x32_bf16 v[24:27], v[156:159], v[214:217], v[24:27]
	v_mfma_f32_16x16x32_bf16 v[24:27], v[152:155], v[206:209], v[24:27]
	v_mfma_f32_16x16x32_bf16 v[12:15], v[152:155], v[210:213], v[12:15]
	v_mfma_f32_16x16x32_bf16 v[12:15], v[156:159], v[218:221], v[12:15]
	v_mfma_f32_16x16x32_bf16 v[16:19], v[148:151], v[218:221], v[16:19]
	v_mfma_f32_16x16x32_bf16 v[16:19], v[144:147], v[210:213], v[16:19]
	s_setprio 0
	s_add_i32 s56, s56, 2
	s_add_u32 s22, s22, 0x100
	s_addc_u32 s23, s23, 0
	s_add_u32 s54, s54, 0x100
	s_addc_u32 s55, s55, 0
	s_cmpk_gt_u32 s56, 0xa9
	s_barrier
	s_cbranch_scc0 .LBB0_1096
	s_and_b64 vcc, exec, s[8:9]
	s_cbranch_vccz .LBB0_1099
	s_barrier
